# plus ztrans and sgu tile loads un-serialized, resid gate loads hoisted, sgu bias loaded once
# speedup vs baseline: 1.0276x; 1.0007x over previous
.LBB0_780:
	s_lshr_b32 s1, s15, 1
	s_lshl_b32 s0, s0, 8
	s_and_b32 s1, s1, 0x60
	v_and_b32_e32 v98, 15, v96
	s_or_b32 s0, s1, s0
	v_lshrrev_b32_e32 v96, 2, v96
	v_and_or_b32 v96, v96, 12, s0
	s_lshl_b64 s[0:1], s[42:43], 12
	s_add_u32 s0, s40, s0
	s_addc_u32 s1, s41, s1
	s_lshr_b32 s6, s48, 12
	s_add_i32 s11, s6, 1
	s_and_b64 s[6:7], s[38:39], exec
	s_cselect_b32 s6, 0, s11
	s_mul_hi_u32 s7, s6, 0x6000
	s_mulk_i32 s6, 0x6000
	v_ashrrev_i32_e32 v97, 31, v96
	s_add_u32 s6, s2, s6
	s_addc_u32 s7, s22, s7
	v_lshlrev_b64 v[146:147], 2, v[96:97]
	v_lshl_add_u64 v[186:187], s[6:7], 0, v[146:147]
	s_ashr_i32 s6, s15, 2
	s_andn2_b32 s6, s6, 63
	v_or_b32_e32 v152, s6, v98
	v_ashrrev_i32_e32 v153, 31, v152
	v_lshl_add_u64 v[150:151], s[0:1], 0, v[146:147]
	v_lshlrev_b64 v[96:97], 12, v[152:153]
	v_lshl_add_u64 v[142:143], v[150:151], 0, v[96:97]
	v_or_b32_e32 v96, 16, v152
	v_ashrrev_i32_e32 v97, 31, v96
	v_lshlrev_b64 v[96:97], 12, v[96:97]
	s_add_i32 s6, s6, s10
	v_lshl_add_u64 v[96:97], v[150:151], 0, v[96:97]
	v_or_b32_e32 v148, s6, v98
	global_load_dwordx4 v[156:159], v[142:143], off nt
	global_load_dwordx4 v[160:163], v[142:143], off offset:64 nt
	global_load_dwordx4 v[166:169], v[142:143], off offset:512 nt
	global_load_dwordx4 v[170:173], v[142:143], off offset:576 nt
	global_load_dwordx4 v[174:177], v[96:97], off nt
	global_load_dwordx4 v[178:181], v[96:97], off offset:64 nt
	global_load_dwordx4 v[182:185], v[96:97], off offset:512 nt
	global_load_dwordx4 v[198:201], v[96:97], off offset:576 nt
	v_ashrrev_i32_e32 v149, 31, v148
	global_load_dwordx4 v[96:99], v[186:187], off
	global_load_dwordx4 v[202:205], v[186:187], off offset:64
	global_load_dwordx4 v[206:209], v[186:187], off offset:512
	global_load_dwordx4 v[210:213], v[186:187], off offset:576
	v_lshlrev_b64 v[144:145], 12, v[148:149]
	v_lshl_add_u64 v[144:145], s[4:5], 0, v[144:145]
	v_lshl_add_u64 v[144:145], v[144:145], 0, v[146:147]
	s_mov_b32 s0, 0x80000
	s_mov_b64 s[6:7], 0x80000
	s_mov_b32 s1, 0x90000
	s_mov_b64 s[10:11], 0x90000
	s_mov_b32 s67, 0xb0000
	s_mov_b64 s[38:39], s[20:21]
	s_waitcnt vmcnt(0)
	v_pk_fma_f32 v[158:159], v[102:103], v[98:99], v[158:159]
	v_pk_fma_f32 v[156:157], v[100:101], v[96:97], v[156:157]
	v_mov_b32_e32 v100, v202
	v_mov_b32_e32 v101, v203
	v_mov_b32_e32 v102, v204
	v_mov_b32_e32 v103, v205
	v_pk_fma_f32 v[162:163], v[106:107], v[102:103], v[162:163]
	v_pk_fma_f32 v[160:161], v[104:105], v[100:101], v[160:161]
	v_mov_b32_e32 v104, v206
	v_mov_b32_e32 v105, v207
	v_mov_b32_e32 v106, v208
	v_mov_b32_e32 v107, v209
	v_pk_fma_f32 v[168:169], v[110:111], v[106:107], v[168:169]
	v_pk_fma_f32 v[166:167], v[108:109], v[104:105], v[166:167]
	v_mov_b32_e32 v108, v210
	v_mov_b32_e32 v109, v211
	v_mov_b32_e32 v110, v212
	v_mov_b32_e32 v111, v213
	s_nop 0
	global_store_dwordx4 v[144:145], v[156:159], off nt
	global_store_dwordx4 v[144:145], v[160:163], off offset:64 nt
	global_store_dwordx4 v[144:145], v[166:169], off offset:512 nt
	v_pk_fma_f32 v[118:119], v[118:119], v[106:107], v[184:185]
	v_pk_fma_f32 v[116:117], v[116:117], v[104:105], v[182:183]
	v_or_b32_e32 v166, 32, v148
	v_ashrrev_i32_e32 v167, 31, v166
	v_lshlrev_b64 v[166:167], 12, v[166:167]
	v_lshl_add_u64 v[166:167], s[4:5], 0, v[166:167]
	v_lshl_add_u64 v[166:167], v[166:167], 0, v[146:147]
	v_pk_fma_f32 v[122:123], v[122:123], v[110:111], v[172:173]
	v_pk_fma_f32 v[120:121], v[120:121], v[108:109], v[170:171]
	global_store_dwordx4 v[144:145], v[120:123], off offset:576 nt
	v_pk_fma_f32 v[114:115], v[114:115], v[110:111], v[200:201]
	v_pk_fma_f32 v[112:113], v[112:113], v[108:109], v[198:199]
	v_or_b32_e32 v120, 16, v148
	v_ashrrev_i32_e32 v121, 31, v120
	v_lshlrev_b64 v[120:121], 12, v[120:121]
	v_lshl_add_u64 v[120:121], s[4:5], 0, v[120:121]
	v_lshl_add_u64 v[156:157], v[120:121], 0, v[146:147]
	global_store_dwordx4 v[156:157], v[112:115], off offset:576 nt
	v_pk_fma_f32 v[122:123], v[130:131], v[98:99], v[176:177]
	v_pk_fma_f32 v[120:121], v[128:129], v[96:97], v[174:175]
	v_or_b32_e32 v112, 32, v152
	v_ashrrev_i32_e32 v113, 31, v112
	global_store_dwordx4 v[156:157], v[120:123], off nt
	v_lshlrev_b64 v[112:113], 12, v[112:113]
	global_store_dwordx4 v[156:157], v[116:119], off offset:512 nt
	v_pk_fma_f32 v[122:123], v[126:127], v[102:103], v[180:181]
	v_pk_fma_f32 v[120:121], v[124:125], v[100:101], v[178:179]
	global_store_dwordx4 v[156:157], v[120:123], off offset:64 nt
	v_lshl_add_u64 v[124:125], v[150:151], 0, v[112:113]
	global_load_dwordx4 v[112:115], v[124:125], off nt
	global_load_dwordx4 v[116:119], v[124:125], off offset:64 nt
	global_load_dwordx4 v[120:123], v[124:125], off offset:512 nt
	s_nop 0
	global_load_dwordx4 v[124:127], v[124:125], off offset:576 nt
	v_or_b32_e32 v128, 48, v152
	v_ashrrev_i32_e32 v129, 31, v128
	v_lshlrev_b64 v[128:129], 12, v[128:129]
	v_lshl_add_u64 v[160:161], v[150:151], 0, v[128:129]
	global_load_dwordx4 v[128:131], v[160:161], off nt
	global_load_dwordx4 v[150:153], v[160:161], off offset:64 nt
	global_load_dwordx4 v[156:159], v[160:161], off offset:512 nt
	s_nop 0
	global_load_dwordx4 v[160:163], v[160:161], off offset:576 nt
	s_waitcnt vmcnt(0)
	v_pk_fma_f32 v[94:95], v[94:95], v[98:99], v[114:115]
	v_pk_fma_f32 v[92:93], v[92:93], v[96:97], v[112:113]
	v_pk_fma_f32 v[90:91], v[90:91], v[102:103], v[118:119]
	v_pk_fma_f32 v[82:83], v[82:83], v[110:111], v[126:127]
	v_pk_fma_f32 v[80:81], v[80:81], v[108:109], v[124:125]
	global_store_dwordx4 v[166:167], v[80:83], off offset:576 nt
	v_pk_fma_f32 v[88:89], v[88:89], v[100:101], v[116:117]
	v_pk_fma_f32 v[86:87], v[86:87], v[106:107], v[122:123]
	v_or_b32_e32 v80, 48, v148
	v_ashrrev_i32_e32 v81, 31, v80
	v_lshlrev_b64 v[80:81], 12, v[80:81]
	v_lshl_add_u64 v[80:81], s[4:5], 0, v[80:81]
	v_lshl_add_u64 v[80:81], v[80:81], 0, v[146:147]
	v_pk_fma_f32 v[66:67], v[66:67], v[110:111], v[162:163]
	v_pk_fma_f32 v[64:65], v[64:65], v[108:109], v[160:161]
	global_store_dwordx4 v[80:81], v[64:67], off offset:576 nt
	v_pk_fma_f32 v[84:85], v[84:85], v[104:105], v[120:121]
	v_pk_fma_f32 v[78:79], v[78:79], v[98:99], v[130:131]
	v_add_co_u32_e32 v64, vcc, s0, v142
	v_pk_fma_f32 v[76:77], v[76:77], v[96:97], v[128:129]
	v_pk_fma_f32 v[74:75], v[74:75], v[102:103], v[152:153]
	v_pk_fma_f32 v[72:73], v[72:73], v[100:101], v[150:151]
	v_pk_fma_f32 v[70:71], v[70:71], v[106:107], v[158:159]
	v_pk_fma_f32 v[68:69], v[68:69], v[104:105], v[156:157]
	v_addc_co_u32_e32 v65, vcc, 0, v143, vcc
	global_store_dwordx4 v[166:167], v[92:95], off nt
	global_store_dwordx4 v[166:167], v[88:91], off offset:64 nt
	global_store_dwordx4 v[166:167], v[84:87], off offset:512 nt
	global_store_dwordx4 v[80:81], v[76:79], off nt
	global_store_dwordx4 v[80:81], v[72:75], off offset:64 nt
	global_store_dwordx4 v[80:81], v[68:71], off offset:512 nt
	v_lshl_add_u64 v[76:77], v[142:143], 0, s[6:7]
	v_add_co_u32_e32 v80, vcc, s1, v142
	global_load_dwordx4 v[64:67], v[64:65], off nt
	s_nop 0
	global_load_dwordx4 v[68:71], v[76:77], off offset:64 nt
	global_load_dwordx4 v[72:75], v[76:77], off offset:512 nt
	s_nop 0
	global_load_dwordx4 v[76:79], v[76:77], off offset:576 nt
	v_lshl_add_u64 v[92:93], v[142:143], 0, s[10:11]
	v_addc_co_u32_e32 v81, vcc, 0, v143, vcc
	global_load_dwordx4 v[80:83], v[80:81], off nt
	s_nop 0
	global_load_dwordx4 v[84:87], v[92:93], off offset:64 nt
	global_load_dwordx4 v[88:91], v[92:93], off offset:512 nt
	s_nop 0
	global_load_dwordx4 v[92:95], v[92:93], off offset:576 nt
	v_lshl_add_u64 v[112:113], v[144:145], 0, s[6:7]
	s_mov_b64 s[6:7], 0xa0000
	s_waitcnt vmcnt(0)
	v_pk_fma_f32 v[60:61], v[60:61], v[96:97], v[64:65]
	v_add_co_u32_e32 v64, vcc, s0, v144
	v_pk_fma_f32 v[46:47], v[46:47], v[106:107], v[74:75]
	s_nop 0
	v_addc_co_u32_e32 v65, vcc, 0, v145, vcc
	v_pk_fma_f32 v[44:45], v[44:45], v[104:105], v[72:73]
	global_store_dwordx4 v[112:113], v[44:47], off offset:512 nt
	v_pk_fma_f32 v[42:43], v[42:43], v[110:111], v[78:79]
	v_pk_fma_f32 v[40:41], v[40:41], v[108:109], v[76:77]
	v_add_co_u32_e32 v46, vcc, s1, v144
	global_store_dwordx4 v[112:113], v[40:43], off offset:576 nt
	v_lshl_add_u64 v[44:45], v[144:145], 0, s[10:11]
	v_addc_co_u32_e32 v47, vcc, 0, v145, vcc
	v_pk_fma_f32 v[42:43], v[54:55], v[98:99], v[82:83]
	v_pk_fma_f32 v[40:41], v[52:53], v[96:97], v[80:81]
	v_pk_fma_f32 v[34:35], v[34:35], v[110:111], v[94:95]
	v_pk_fma_f32 v[32:33], v[32:33], v[108:109], v[92:93]
	s_mov_b32 s0, 0xa0000
	v_pk_fma_f32 v[62:63], v[62:63], v[98:99], v[66:67]
	v_pk_fma_f32 v[58:59], v[58:59], v[102:103], v[70:71]
	v_pk_fma_f32 v[56:57], v[56:57], v[100:101], v[68:69]
	global_store_dwordx4 v[46:47], v[40:43], off nt
	v_pk_fma_f32 v[38:39], v[38:39], v[106:107], v[90:91]
	v_pk_fma_f32 v[36:37], v[36:37], v[104:105], v[88:89]
	v_pk_fma_f32 v[42:43], v[50:51], v[102:103], v[86:87]
	v_pk_fma_f32 v[40:41], v[48:49], v[100:101], v[84:85]
	global_store_dwordx4 v[44:45], v[32:35], off offset:576 nt
	global_store_dwordx4 v[64:65], v[60:63], off nt
	global_store_dwordx4 v[112:113], v[56:59], off offset:64 nt
	v_add_co_u32_e32 v32, vcc, s0, v142
	global_store_dwordx4 v[44:45], v[40:43], off offset:64 nt
	global_store_dwordx4 v[44:45], v[36:39], off offset:512 nt
	v_lshl_add_u64 v[44:45], v[142:143], 0, s[6:7]
	v_addc_co_u32_e32 v33, vcc, 0, v143, vcc
	s_mov_b32 s1, 0xb0000
	global_load_dwordx4 v[32:35], v[32:33], off nt
	s_nop 0
	global_load_dwordx4 v[36:39], v[44:45], off offset:64 nt
	global_load_dwordx4 v[40:43], v[44:45], off offset:512 nt
	s_nop 0
	global_load_dwordx4 v[44:47], v[44:45], off offset:576 nt
	s_mov_b64 s[10:11], 0xb0000
	v_add_co_u32_e32 v48, vcc, s1, v142
	v_lshl_add_u64 v[60:61], v[142:143], 0, s[10:11]
	s_nop 0
	v_addc_co_u32_e32 v49, vcc, 0, v143, vcc
	global_load_dwordx4 v[48:51], v[48:49], off nt
	s_nop 0
	global_load_dwordx4 v[52:55], v[60:61], off offset:64 nt
	global_load_dwordx4 v[56:59], v[60:61], off offset:512 nt
	s_nop 0
	global_load_dwordx4 v[60:63], v[60:61], off offset:576 nt
	v_lshl_add_u64 v[64:65], v[144:145], 0, s[6:7]
	s_waitcnt vmcnt(0)
	v_pk_fma_f32 v[28:29], v[28:29], v[96:97], v[32:33]
	v_add_co_u32_e32 v32, vcc, s0, v144
	v_pk_fma_f32 v[14:15], v[14:15], v[106:107], v[42:43]
	s_nop 0
	v_addc_co_u32_e32 v33, vcc, 0, v145, vcc
	v_pk_fma_f32 v[12:13], v[12:13], v[104:105], v[40:41]
	global_store_dwordx4 v[64:65], v[12:15], off offset:512 nt
	v_pk_fma_f32 v[10:11], v[10:11], v[110:111], v[46:47]
	v_pk_fma_f32 v[8:9], v[8:9], v[108:109], v[44:45]
	v_add_co_u32_e32 v14, vcc, s1, v144
	global_store_dwordx4 v[64:65], v[8:11], off offset:576 nt
	s_nop 0
	v_addc_co_u32_e32 v15, vcc, 0, v145, vcc
	v_pk_fma_f32 v[10:11], v[22:23], v[98:99], v[50:51]
	v_pk_fma_f32 v[8:9], v[20:21], v[96:97], v[48:49]
	v_pk_fma_f32 v[30:31], v[30:31], v[98:99], v[34:35]
	v_pk_fma_f32 v[26:27], v[26:27], v[102:103], v[38:39]
	v_pk_fma_f32 v[24:25], v[24:25], v[100:101], v[36:37]
	v_lshl_add_u64 v[12:13], v[144:145], 0, s[10:11]
	global_store_dwordx4 v[14:15], v[8:11], off nt
	v_pk_fma_f32 v[6:7], v[6:7], v[106:107], v[58:59]
	v_pk_fma_f32 v[4:5], v[4:5], v[104:105], v[56:57]
	v_pk_fma_f32 v[10:11], v[18:19], v[102:103], v[54:55]
	v_pk_fma_f32 v[8:9], v[16:17], v[100:101], v[52:53]
	v_pk_fma_f32 v[2:3], v[2:3], v[110:111], v[62:63]
	v_pk_fma_f32 v[0:1], v[0:1], v[108:109], v[60:61]
	s_and_b64 vcc, exec, s[36:37]
	s_mov_b32 s1, s14
	s_mov_b32 s0, s16
	s_mov_b64 s[10:11], s[30:31]
	global_store_dwordx4 v[32:33], v[28:31], off nt
	global_store_dwordx4 v[64:65], v[24:27], off offset:64 nt
	global_store_dwordx4 v[12:13], v[8:11], off offset:64 nt
	global_store_dwordx4 v[12:13], v[4:7], off offset:512 nt
	global_store_dwordx4 v[12:13], v[0:3], off offset:576 nt
	s_cbranch_vccnz .LBB0_797

.LBB0_958:
	s_mul_hi_i32 s0, s16, 0x66666667
	s_lshr_b32 s1, s0, 31
	s_ashr_i32 s0, s0, 6
	s_add_i32 s8, s0, s1
	s_ashr_i32 s9, s8, 31
	s_mul_i32 s1, s8, 0xa00000
	s_mul_hi_i32 s0, s8, 0xa00000
	s_add_u32 s10, s2, s1
	s_addc_u32 s11, s6, s0
	s_lshl_b64 s[0:1], s[8:9], 15
	v_mov_b32_e32 v64, v188
	s_add_u32 s20, s7, s0
	s_mul_i32 s0, s8, 0xa000
	v_ashrrev_i32_e32 v4, 3, v64
	v_subrev_u32_e32 v0, s0, v4
	v_add_u32_e32 v0, s15, v0
	v_ashrrev_i32_e32 v1, 31, v0
	v_ashrrev_i32_e32 v5, 31, v4
	v_lshlrev_b64 v[2:3], 8, v[0:1]
	v_lshlrev_b64 v[0:1], 8, v[4:5]
	v_lshlrev_b32_e32 v5, 4, v64
	v_and_b32_e32 v164, 0x70, v5
	v_xor_b32_e32 v5, v4, v64
	v_lshl_add_u64 v[2:3], s[10:11], 0, v[2:3]
	v_lshlrev_b32_e32 v5, 4, v5
	v_lshl_add_u64 v[2:3], v[2:3], 0, v[164:165]
	v_lshlrev_b32_e32 v4, 7, v4
	v_and_or_b32 v18, v5, s22, v4
	global_load_dwordx4 v[198:201], v[2:3], off
	v_add_u32_e32 v12, 0, v18
	s_addc_u32 s21, s12, s1
	s_mov_b32 s1, 0xc000
	v_lshl_add_u64 v[0:1], s[20:21], 0, v[0:1]
	v_lshl_add_u64 v[0:1], v[0:1], 0, v[164:165]
	v_lshrrev_b32_e32 v13, 4, v64
	v_and_b32_e32 v62, 7, v64
	v_bitop3_b32 v13, v13, v62, 3 bitop3:0x6c
	v_bfe_u32 v66, v64, 6, 1
	v_and_b32_e32 v67, 15, v64
	v_ashrrev_i32_e32 v128, 7, v64
	v_lshlrev_b32_e32 v13, 4, v13
	v_add_u32_e32 v30, 0, v13
	v_lshlrev_b32_e32 v88, 13, v128
	v_lshlrev_b32_e32 v117, 7, v67
	v_lshlrev_b32_e32 v119, 13, v66
	v_add3_u32 v118, v30, v88, v117
	v_add3_u32 v42, v30, v119, v117
	v_bfe_u32 v65, v64, 4, 2
	v_add_u32_e32 v63, 0xc000, v12
	s_lshl_b32 s8, s8, 7
	s_ashr_i32 s9, s8, 31
	v_and_b32_e32 v64, 0x80, v64
	v_lshl_or_b32 v164, v65, 3, v64
	v_add_co_u32_e32 v4, vcc, s27, v2
	s_nop 1
	v_addc_co_u32_e32 v5, vcc, 0, v3, vcc
	global_load_dwordx4 v[202:205], v[4:5], off
	v_add_co_u32_e32 v6, vcc, s25, v2
	s_nop 1
	v_addc_co_u32_e32 v7, vcc, 0, v3, vcc
	global_load_dwordx4 v[206:209], v[6:7], off
	v_add_co_u32_e32 v8, vcc, s1, v2
	s_add_i32 s1, 0, 0x14000
	s_nop 0
	v_addc_co_u32_e32 v9, vcc, 0, v3, vcc
	global_load_dwordx4 v[210:213], v[8:9], off
	v_add_co_u32_e32 v10, vcc, s27, v0
	v_add_u32_e32 v116, s1, v18
	s_nop 0
	v_addc_co_u32_e32 v11, vcc, 0, v1, vcc
	global_load_dwordx4 v[214:217], v[0:1], off
	global_load_dwordx4 v[218:221], v[10:11], off
	s_waitcnt vmcnt(5)
	ds_write_b128 v12, v[198:201]
	s_waitcnt vmcnt(4)
	ds_write_b128 v12, v[202:205] offset:8192
	s_waitcnt vmcnt(3)
	ds_write_b128 v12, v[206:209] offset:16384
	s_waitcnt vmcnt(2)
	ds_write_b128 v12, v[210:213] offset:24576
	s_waitcnt vmcnt(1)
	ds_write_b128 v12, v[214:217] offset:32768
	s_waitcnt vmcnt(0)
	ds_write_b128 v12, v[218:221] offset:40960
	s_waitcnt lgkmcnt(0)
	s_barrier
	ds_read_b128 v[14:17], v118
	ds_read_b128 v[18:21], v118 offset:2048
	ds_read_b128 v[22:25], v118 offset:4096
	ds_read_b128 v[26:29], v118 offset:6144
	ds_read_b128 v[30:33], v42 offset:32768
	ds_read_b128 v[34:37], v42 offset:34816
	ds_read_b128 v[38:41], v42 offset:36864
	ds_read_b128 v[42:45], v42 offset:38912
	s_waitcnt lgkmcnt(3)
	v_mfma_f32_16x16x32_bf16 v[46:49], v[14:17], v[30:33], 0
	s_waitcnt lgkmcnt(2)
	v_mfma_f32_16x16x32_bf16 v[50:53], v[14:17], v[34:37], 0
	s_waitcnt lgkmcnt(1)
	v_mfma_f32_16x16x32_bf16 v[54:57], v[14:17], v[38:41], 0
	s_waitcnt lgkmcnt(0)
	v_mfma_f32_16x16x32_bf16 v[14:17], v[14:17], v[42:45], 0
	v_mfma_f32_16x16x32_bf16 v[58:61], v[18:21], v[30:33], 0
	v_mfma_f32_16x16x32_bf16 v[68:71], v[18:21], v[34:37], 0
	v_mfma_f32_16x16x32_bf16 v[72:75], v[18:21], v[38:41], 0
	v_mfma_f32_16x16x32_bf16 v[18:21], v[18:21], v[42:45], 0
	v_mfma_f32_16x16x32_bf16 v[76:79], v[22:25], v[30:33], 0
	v_mfma_f32_16x16x32_bf16 v[80:83], v[22:25], v[34:37], 0
	v_mfma_f32_16x16x32_bf16 v[84:87], v[22:25], v[38:41], 0
	v_mfma_f32_16x16x32_bf16 v[22:25], v[22:25], v[42:45], 0
	v_mfma_f32_16x16x32_bf16 v[30:33], v[26:29], v[30:33], 0
	v_mfma_f32_16x16x32_bf16 v[34:37], v[26:29], v[34:37], 0
	v_mfma_f32_16x16x32_bf16 v[38:41], v[26:29], v[38:41], 0
	v_mfma_f32_16x16x32_bf16 v[26:29], v[26:29], v[42:45], 0
	v_bitop3_b32 v42, v65, v62, 4 bitop3:0x36
	v_lshlrev_b32_e32 v62, 4, v42
	v_add_u32_e32 v100, 0, v62
	v_add3_u32 v120, v100, v88, v117
	v_add3_u32 v112, v100, v119, v117
	ds_read_b128 v[42:45], v120
	ds_read_b128 v[88:91], v120 offset:2048
	ds_read_b128 v[92:95], v120 offset:4096
	ds_read_b128 v[96:99], v120 offset:6144
	ds_read_b128 v[100:103], v112 offset:32768
	ds_read_b128 v[104:107], v112 offset:34816
	ds_read_b128 v[108:111], v112 offset:36864
	ds_read_b128 v[112:115], v112 offset:38912
	s_waitcnt lgkmcnt(3)
	v_mfma_f32_16x16x32_bf16 v[46:49], v[42:45], v[100:103], v[46:49]
	s_waitcnt lgkmcnt(2)
	v_mfma_f32_16x16x32_bf16 v[50:53], v[42:45], v[104:107], v[50:53]
	s_waitcnt lgkmcnt(1)
	v_mfma_f32_16x16x32_bf16 v[54:57], v[42:45], v[108:111], v[54:57]
	s_waitcnt lgkmcnt(0)
	v_mfma_f32_16x16x32_bf16 v[14:17], v[42:45], v[112:115], v[14:17]
	v_mfma_f32_16x16x32_bf16 v[42:45], v[88:91], v[100:103], v[58:61]
	v_mfma_f32_16x16x32_bf16 v[58:61], v[88:91], v[104:107], v[68:71]
	v_mfma_f32_16x16x32_bf16 v[68:71], v[88:91], v[108:111], v[72:75]
	v_mfma_f32_16x16x32_bf16 v[72:75], v[92:95], v[100:103], v[76:79]
	v_mfma_f32_16x16x32_bf16 v[76:79], v[92:95], v[104:107], v[80:83]
	v_mfma_f32_16x16x32_bf16 v[80:83], v[92:95], v[108:111], v[84:87]
	s_nop 2
	global_load_dwordx4 v[198:201], v[2:3], off offset:128
	global_load_dwordx4 v[202:205], v[4:5], off offset:128
	global_load_dwordx4 v[206:209], v[6:7], off offset:128
	global_load_dwordx4 v[210:213], v[8:9], off offset:128
	global_load_dwordx4 v[214:217], v[0:1], off offset:128
	global_load_dwordx4 v[218:221], v[10:11], off offset:128
	v_mfma_f32_16x16x32_bf16 v[18:21], v[88:91], v[112:115], v[18:21]
	v_mfma_f32_16x16x32_bf16 v[22:25], v[92:95], v[112:115], v[22:25]
	v_mfma_f32_16x16x32_bf16 v[30:33], v[96:99], v[100:103], v[30:33]
	v_mfma_f32_16x16x32_bf16 v[34:37], v[96:99], v[104:107], v[34:37]
	v_mfma_f32_16x16x32_bf16 v[38:41], v[96:99], v[108:111], v[38:41]
	v_mfma_f32_16x16x32_bf16 v[26:29], v[96:99], v[112:115], v[26:29]
	s_waitcnt vmcnt(5)
	ds_write_b128 v12, v[198:201] offset:49152
	s_waitcnt vmcnt(4)
	ds_write_b128 v12, v[202:205] offset:57344
	v_add_u32_e32 v12, s1, v13
	v_add3_u32 v12, v12, v119, v117
	s_waitcnt vmcnt(3)
	ds_write_b128 v63, v[206:209] offset:16384
	s_waitcnt vmcnt(2)
	ds_write_b128 v63, v[210:213] offset:24576
	s_waitcnt vmcnt(1)
	ds_write_b128 v116, v[214:217]
	s_waitcnt vmcnt(0)
	ds_write_b128 v116, v[218:221] offset:8192
	s_waitcnt lgkmcnt(0)
	s_barrier
	ds_read_b128 v[0:3], v118 offset:49152
	ds_read_b128 v[4:7], v118 offset:51200
	ds_read_b128 v[8:11], v118 offset:53248
	ds_read_b128 v[84:87], v118 offset:55296
	ds_read_b128 v[88:91], v12
	ds_read_b128 v[92:95], v12 offset:2048
	ds_read_b128 v[96:99], v12 offset:4096
	ds_read_b128 v[100:103], v12 offset:6144
	s_waitcnt lgkmcnt(3)
	v_mfma_f32_16x16x32_bf16 v[46:49], v[0:3], v[88:91], v[46:49]
	s_waitcnt lgkmcnt(2)
	v_mfma_f32_16x16x32_bf16 v[50:53], v[0:3], v[92:95], v[50:53]
	s_waitcnt lgkmcnt(1)
	v_mfma_f32_16x16x32_bf16 v[104:107], v[0:3], v[96:99], v[54:57]
	s_waitcnt lgkmcnt(0)
	v_mfma_f32_16x16x32_bf16 v[0:3], v[0:3], v[100:103], v[14:17]
	v_mfma_f32_16x16x32_bf16 v[12:15], v[4:7], v[88:91], v[42:45]
	v_mfma_f32_16x16x32_bf16 v[108:111], v[4:7], v[92:95], v[58:61]
	v_mfma_f32_16x16x32_bf16 v[68:71], v[4:7], v[96:99], v[68:71]
	v_mfma_f32_16x16x32_bf16 v[4:7], v[4:7], v[100:103], v[18:21]
	v_mfma_f32_16x16x32_bf16 v[16:19], v[8:11], v[88:91], v[72:75]
	v_mfma_f32_16x16x32_bf16 v[72:75], v[8:11], v[92:95], v[76:79]
	v_mfma_f32_16x16x32_bf16 v[76:79], v[8:11], v[96:99], v[80:83]
	v_mfma_f32_16x16x32_bf16 v[80:83], v[84:87], v[88:91], v[30:33]
	v_mfma_f32_16x16x32_bf16 v[88:91], v[84:87], v[92:95], v[34:37]
	v_mfma_f32_16x16x32_bf16 v[92:95], v[84:87], v[96:99], v[38:41]
	v_mfma_f32_16x16x32_bf16 v[84:87], v[84:87], v[100:103], v[26:29]
	s_nop 2
	v_add_u32_e32 v28, s1, v62
	v_add3_u32 v28, v28, v119, v117
	v_mfma_f32_16x16x32_bf16 v[8:11], v[8:11], v[100:103], v[22:25]
	s_nop 2
	ds_read_b128 v[20:23], v120 offset:49152
	ds_read_b128 v[24:27], v120 offset:51200
	ds_read_b128 v[96:99], v120 offset:53248
	ds_read_b128 v[100:103], v120 offset:55296
	ds_read_b128 v[112:115], v28
	ds_read_b128 v[116:119], v28 offset:2048
	ds_read_b128 v[120:123], v28 offset:4096
	ds_read_b128 v[124:127], v28 offset:6144
	s_waitcnt lgkmcnt(0)
	v_mfma_f32_16x16x32_bf16 v[36:39], v[24:27], v[120:123], v[68:71]
	s_barrier
	s_nop 1
	v_lshlrev_b32_e32 v68, 6, v128
	v_subrev_u32_e32 v68, s0, v68
	s_lshl_b64 s[0:1], s[8:9], 1
	v_mfma_f32_16x16x32_bf16 v[60:63], v[20:23], v[112:115], v[46:49]
	v_add_u32_e32 v68, s15, v68
	s_add_u32 s10, s13, s0
	s_movk_i32 s0, 0xff80
	v_mfma_f32_16x16x32_bf16 v[56:59], v[20:23], v[116:119], v[50:53]
	s_addc_u32 s11, s14, s1
	v_lshl_add_u64 v[70:71], s[10:11], 0, v[164:165]
	v_mfma_f32_16x16x32_bf16 v[48:51], v[20:23], v[124:127], v[0:3]
	s_add_i32 s16, s16, s3
	s_add_i32 s15, s15, s17
	s_cmpk_lt_i32 s16, 0x280
	v_mfma_f32_16x16x32_bf16 v[0:3], v[100:103], v[124:127], v[84:87]
	s_nop 2
	v_lshl_or_b32 v86, v66, 6, v67
	v_and_or_b32 v68, v68, s0, v86
	v_ashrrev_i32_e32 v69, 31, v68
	v_lshlrev_b64 v[64:65], 11, v[68:69]
	v_mfma_f32_16x16x32_bf16 v[44:47], v[24:27], v[112:115], v[12:15]
	v_mfma_f32_16x16x32_bf16 v[40:43], v[24:27], v[116:119], v[108:111]
	v_mfma_f32_16x16x32_bf16 v[32:35], v[24:27], v[124:127], v[4:7]
	v_mfma_f32_16x16x32_bf16 v[24:27], v[96:99], v[116:119], v[72:75]
	s_nop 2
	v_lshl_add_u64 v[72:73], v[70:71], 0, v[64:65]
	v_or_b32_e32 v64, 16, v68
	v_ashrrev_i32_e32 v65, 31, v64
	v_lshlrev_b64 v[64:65], 11, v[64:65]
	v_lshl_add_u64 v[66:67], v[70:71], 0, v[64:65]
	v_or_b32_e32 v64, 32, v68
	v_or_b32_e32 v68, 48, v68
	v_mfma_f32_16x16x32_bf16 v[52:55], v[20:23], v[120:123], v[104:107]
	v_ashrrev_i32_e32 v65, 31, v64
	v_ashrrev_i32_e32 v69, 31, v68
	v_lshlrev_b64 v[64:65], 11, v[64:65]
	v_or_b32_e32 v106, s8, v86
	v_lshlrev_b64 v[68:69], 11, v[68:69]
	v_ashrrev_i32_e32 v107, 31, v106
	v_lshl_add_u64 v[64:65], v[70:71], 0, v[64:65]
	v_lshl_add_u64 v[68:69], v[70:71], 0, v[68:69]
	v_lshl_add_u64 v[86:87], v[106:107], 2, s[4:5]
	v_mfma_f32_16x16x32_bf16 v[28:31], v[96:99], v[112:115], v[16:19]
	global_load_dwordx2 v[104:105], v[72:73], off
	v_mfma_f32_16x16x32_bf16 v[20:23], v[96:99], v[120:123], v[76:79]
	v_mfma_f32_16x16x32_bf16 v[16:19], v[96:99], v[124:127], v[8:11]
	global_load_dwordx2 v[98:99], v[64:65], off
	v_mfma_f32_16x16x32_bf16 v[12:15], v[100:103], v[112:115], v[80:83]
	v_mfma_f32_16x16x32_bf16 v[8:11], v[100:103], v[116:119], v[88:91]
	v_mfma_f32_16x16x32_bf16 v[4:7], v[100:103], v[120:123], v[92:95]
	global_load_dwordx2 v[102:103], v[66:67], off
	global_load_dwordx2 v[100:101], v[68:69], off
	global_load_dwordx2 v[96:97], v[72:73], off offset:32
	global_load_dwordx2 v[94:95], v[66:67], off offset:32
	global_load_dwordx2 v[92:93], v[64:65], off offset:32
	global_load_dwordx2 v[90:91], v[68:69], off offset:32
	global_load_dwordx2 v[88:89], v[72:73], off offset:64
	global_load_dwordx2 v[84:85], v[66:67], off offset:64
	global_load_dwordx2 v[82:83], v[64:65], off offset:64
	global_load_dwordx2 v[80:81], v[68:69], off offset:64
	global_load_dwordx2 v[78:79], v[72:73], off offset:96
	global_load_dwordx2 v[76:77], v[66:67], off offset:96
	global_load_dwordx2 v[74:75], v[64:65], off offset:96
	global_load_dwordx2 v[70:71], v[68:69], off offset:96
	global_load_dword v222, v[86:87], off
	global_load_dword v223, v[86:87], off offset:64
	global_load_dword v224, v[86:87], off offset:128
	global_load_dword v225, v[86:87], off offset:192
	s_waitcnt vmcnt(0)
	v_mov_b32_e32 v107, v222
	v_lshlrev_b32_e32 v108, 16, v104
	v_and_b32_e32 v104, 0xffff0000, v104
	s_waitcnt vmcnt(0)
	v_add_f32_e32 v61, v61, v107
	v_add_f32_e32 v60, v60, v107
	v_mul_f32_e32 v61, v61, v104
	v_lshlrev_b32_e32 v104, 16, v105
	v_add_f32_e32 v62, v62, v107
	v_mul_f32_e32 v60, v60, v108
	v_mul_f32_e32 v62, v62, v104
	v_and_b32_e32 v104, 0xffff0000, v105
	v_add_f32_e32 v63, v63, v107
	v_mul_f32_e32 v63, v63, v104
	v_cvt_pk_bf16_f32 v60, v60, v61
	v_cvt_pk_bf16_f32 v61, v62, v63
	v_mov_b32_e32 v107, s9
	global_store_dwordx2 v[72:73], v[60:61], off
	v_lshl_add_u64 v[60:61], v[106:107], 2, s[4:5]
	v_mov_b32_e32 v62, v223
	v_lshlrev_b32_e32 v63, 16, v102
	v_add_f32_e32 v56, v56, v62
	v_mul_f32_e32 v56, v56, v63
	v_and_b32_e32 v63, 0xffff0000, v102
	v_add_f32_e32 v57, v57, v62
	v_mul_f32_e32 v57, v57, v63
	v_lshlrev_b32_e32 v63, 16, v103
	v_add_f32_e32 v58, v58, v62
	v_mul_f32_e32 v58, v58, v63
	v_and_b32_e32 v63, 0xffff0000, v103
	v_add_f32_e32 v59, v59, v62
	v_mul_f32_e32 v59, v59, v63
	v_cvt_pk_bf16_f32 v56, v56, v57
	v_cvt_pk_bf16_f32 v57, v58, v59
	global_store_dwordx2 v[66:67], v[56:57], off
	v_mov_b32_e32 v56, v224
	v_lshlrev_b32_e32 v57, 16, v98
	v_add_f32_e32 v52, v52, v56
	v_mul_f32_e32 v52, v52, v57
	v_and_b32_e32 v57, 0xffff0000, v98
	v_add_f32_e32 v53, v53, v56
	v_mul_f32_e32 v53, v53, v57
	v_lshlrev_b32_e32 v57, 16, v99
	v_add_f32_e32 v54, v54, v56
	v_mul_f32_e32 v54, v54, v57
	v_and_b32_e32 v57, 0xffff0000, v99
	v_add_f32_e32 v55, v55, v56
	v_mul_f32_e32 v55, v55, v57
	v_cvt_pk_bf16_f32 v52, v52, v53
	v_cvt_pk_bf16_f32 v53, v54, v55
	global_store_dwordx2 v[64:65], v[52:53], off
	v_mov_b32_e32 v52, v225
	v_lshlrev_b32_e32 v53, 16, v100
	v_add_f32_e32 v48, v48, v52
	v_mul_f32_e32 v48, v48, v53
	v_and_b32_e32 v53, 0xffff0000, v100
	v_add_f32_e32 v49, v49, v52
	v_mul_f32_e32 v49, v49, v53
	v_lshlrev_b32_e32 v53, 16, v101
	v_add_f32_e32 v50, v50, v52
	v_mul_f32_e32 v50, v50, v53
	v_and_b32_e32 v53, 0xffff0000, v101
	v_add_f32_e32 v51, v51, v52
	v_mul_f32_e32 v51, v51, v53
	v_cvt_pk_bf16_f32 v48, v48, v49
	v_cvt_pk_bf16_f32 v49, v50, v51
	global_store_dwordx2 v[68:69], v[48:49], off
	v_mov_b32_e32 v48, v222
	v_lshlrev_b32_e32 v49, 16, v96
	v_add_f32_e32 v44, v44, v48
	v_mul_f32_e32 v44, v44, v49
	v_and_b32_e32 v49, 0xffff0000, v96
	v_add_f32_e32 v45, v45, v48
	v_mul_f32_e32 v45, v45, v49
	v_lshlrev_b32_e32 v49, 16, v97
	v_add_f32_e32 v46, v46, v48
	v_mul_f32_e32 v46, v46, v49
	v_and_b32_e32 v49, 0xffff0000, v97
	v_add_f32_e32 v47, v47, v48
	v_mul_f32_e32 v47, v47, v49
	v_cvt_pk_bf16_f32 v44, v44, v45
	v_cvt_pk_bf16_f32 v45, v46, v47
	global_store_dwordx2 v[72:73], v[44:45], off offset:32
	v_mov_b32_e32 v44, v223
	v_lshlrev_b32_e32 v45, 16, v94
	v_add_f32_e32 v40, v40, v44
	v_mul_f32_e32 v40, v40, v45
	v_and_b32_e32 v45, 0xffff0000, v94
	v_add_f32_e32 v41, v41, v44
	v_mul_f32_e32 v41, v41, v45
	v_lshlrev_b32_e32 v45, 16, v95
	v_add_f32_e32 v42, v42, v44
	v_mul_f32_e32 v42, v42, v45
	v_and_b32_e32 v45, 0xffff0000, v95
	v_add_f32_e32 v43, v43, v44
	v_mul_f32_e32 v43, v43, v45
	v_cvt_pk_bf16_f32 v40, v40, v41
	v_cvt_pk_bf16_f32 v41, v42, v43
	global_store_dwordx2 v[66:67], v[40:41], off offset:32
	v_mov_b32_e32 v40, v224
	v_lshlrev_b32_e32 v41, 16, v92
	v_add_f32_e32 v36, v36, v40
	v_mul_f32_e32 v36, v36, v41
	v_and_b32_e32 v41, 0xffff0000, v92
	v_add_f32_e32 v37, v37, v40
	v_mul_f32_e32 v37, v37, v41
	v_lshlrev_b32_e32 v41, 16, v93
	v_add_f32_e32 v38, v38, v40
	v_mul_f32_e32 v38, v38, v41
	v_and_b32_e32 v41, 0xffff0000, v93
	v_add_f32_e32 v39, v39, v40
	v_mul_f32_e32 v39, v39, v41
	v_cvt_pk_bf16_f32 v36, v36, v37
	v_cvt_pk_bf16_f32 v37, v38, v39
	global_store_dwordx2 v[64:65], v[36:37], off offset:32
	v_mov_b32_e32 v36, v225
	v_lshlrev_b32_e32 v37, 16, v90
	v_add_f32_e32 v32, v32, v36
	v_mul_f32_e32 v32, v32, v37
	v_and_b32_e32 v37, 0xffff0000, v90
	v_add_f32_e32 v33, v33, v36
	v_mul_f32_e32 v33, v33, v37
	v_lshlrev_b32_e32 v37, 16, v91
	v_add_f32_e32 v34, v34, v36
	v_mul_f32_e32 v34, v34, v37
	v_and_b32_e32 v37, 0xffff0000, v91
	v_add_f32_e32 v35, v35, v36
	v_mul_f32_e32 v35, v35, v37
	v_cvt_pk_bf16_f32 v32, v32, v33
	v_cvt_pk_bf16_f32 v33, v34, v35
	global_store_dwordx2 v[68:69], v[32:33], off offset:32
	v_mov_b32_e32 v32, v222
	v_lshlrev_b32_e32 v33, 16, v88
	v_add_f32_e32 v28, v28, v32
	v_mul_f32_e32 v28, v28, v33
	v_and_b32_e32 v33, 0xffff0000, v88
	v_add_f32_e32 v29, v29, v32
	v_mul_f32_e32 v29, v29, v33
	v_lshlrev_b32_e32 v33, 16, v89
	v_add_f32_e32 v30, v30, v32
	v_mul_f32_e32 v30, v30, v33
	v_and_b32_e32 v33, 0xffff0000, v89
	v_add_f32_e32 v31, v31, v32
	v_mul_f32_e32 v31, v31, v33
	v_cvt_pk_bf16_f32 v28, v28, v29
	v_cvt_pk_bf16_f32 v29, v30, v31
	global_store_dwordx2 v[72:73], v[28:29], off offset:64
	v_mov_b32_e32 v28, v223
	v_lshlrev_b32_e32 v29, 16, v84
	v_add_f32_e32 v24, v24, v28
	v_mul_f32_e32 v24, v24, v29
	v_and_b32_e32 v29, 0xffff0000, v84
	v_add_f32_e32 v25, v25, v28
	v_mul_f32_e32 v25, v25, v29
	v_lshlrev_b32_e32 v29, 16, v85
	v_add_f32_e32 v26, v26, v28
	v_mul_f32_e32 v26, v26, v29
	v_and_b32_e32 v29, 0xffff0000, v85
	v_add_f32_e32 v27, v27, v28
	v_mul_f32_e32 v27, v27, v29
	v_cvt_pk_bf16_f32 v24, v24, v25
	v_cvt_pk_bf16_f32 v25, v26, v27
	global_store_dwordx2 v[66:67], v[24:25], off offset:64
	v_mov_b32_e32 v24, v224
	v_lshlrev_b32_e32 v25, 16, v82
	v_add_f32_e32 v20, v20, v24
	v_mul_f32_e32 v20, v20, v25
	v_and_b32_e32 v25, 0xffff0000, v82
	v_add_f32_e32 v21, v21, v24
	v_mul_f32_e32 v21, v21, v25
	v_lshlrev_b32_e32 v25, 16, v83
	v_add_f32_e32 v22, v22, v24
	v_mul_f32_e32 v22, v22, v25
	v_and_b32_e32 v25, 0xffff0000, v83
	v_add_f32_e32 v23, v23, v24
	v_mul_f32_e32 v23, v23, v25
	v_cvt_pk_bf16_f32 v20, v20, v21
	v_cvt_pk_bf16_f32 v21, v22, v23
	global_store_dwordx2 v[64:65], v[20:21], off offset:64
	v_mov_b32_e32 v20, v225
	v_lshlrev_b32_e32 v21, 16, v80
	v_add_f32_e32 v16, v16, v20
	v_mul_f32_e32 v16, v16, v21
	v_and_b32_e32 v21, 0xffff0000, v80
	v_add_f32_e32 v17, v17, v20
	v_mul_f32_e32 v17, v17, v21
	v_lshlrev_b32_e32 v21, 16, v81
	v_add_f32_e32 v18, v18, v20
	v_mul_f32_e32 v18, v18, v21
	v_and_b32_e32 v21, 0xffff0000, v81
	v_add_f32_e32 v19, v19, v20
	v_mul_f32_e32 v19, v19, v21
	v_cvt_pk_bf16_f32 v16, v16, v17
	v_cvt_pk_bf16_f32 v17, v18, v19
	global_store_dwordx2 v[68:69], v[16:17], off offset:64
	v_mov_b32_e32 v16, v222
	v_lshlrev_b32_e32 v17, 16, v78
	v_add_f32_e32 v12, v12, v16
	v_mul_f32_e32 v12, v12, v17
	v_and_b32_e32 v17, 0xffff0000, v78
	v_add_f32_e32 v13, v13, v16
	v_mul_f32_e32 v13, v13, v17
	v_lshlrev_b32_e32 v17, 16, v79
	v_add_f32_e32 v14, v14, v16
	v_mul_f32_e32 v14, v14, v17
	v_and_b32_e32 v17, 0xffff0000, v79
	v_add_f32_e32 v15, v15, v16
	v_mul_f32_e32 v15, v15, v17
	v_cvt_pk_bf16_f32 v12, v12, v13
	v_cvt_pk_bf16_f32 v13, v14, v15
	global_store_dwordx2 v[72:73], v[12:13], off offset:96
	v_mov_b32_e32 v12, v223
	v_lshlrev_b32_e32 v13, 16, v76
	v_add_f32_e32 v8, v8, v12
	v_mul_f32_e32 v8, v8, v13
	v_and_b32_e32 v13, 0xffff0000, v76
	v_add_f32_e32 v9, v9, v12
	v_mul_f32_e32 v9, v9, v13
	v_lshlrev_b32_e32 v13, 16, v77
	v_add_f32_e32 v10, v10, v12
	v_mul_f32_e32 v10, v10, v13
	v_and_b32_e32 v13, 0xffff0000, v77
	v_add_f32_e32 v11, v11, v12
	v_mul_f32_e32 v11, v11, v13
	v_cvt_pk_bf16_f32 v8, v8, v9
	v_cvt_pk_bf16_f32 v9, v10, v11
	global_store_dwordx2 v[66:67], v[8:9], off offset:96
	v_mov_b32_e32 v8, v224
	v_lshlrev_b32_e32 v9, 16, v74
	v_add_f32_e32 v4, v4, v8
	v_mul_f32_e32 v4, v4, v9
	v_and_b32_e32 v9, 0xffff0000, v74
	v_add_f32_e32 v5, v5, v8
	v_mul_f32_e32 v5, v5, v9
	v_lshlrev_b32_e32 v9, 16, v75
	v_add_f32_e32 v6, v6, v8
	v_mul_f32_e32 v6, v6, v9
	v_and_b32_e32 v9, 0xffff0000, v75
	v_add_f32_e32 v7, v7, v8
	v_mul_f32_e32 v7, v7, v9
	v_cvt_pk_bf16_f32 v4, v4, v5
	v_cvt_pk_bf16_f32 v5, v6, v7
	global_store_dwordx2 v[64:65], v[4:5], off offset:96
	v_mov_b32_e32 v4, v225
	v_lshlrev_b32_e32 v5, 16, v70
	v_add_f32_e32 v0, v0, v4
	v_mul_f32_e32 v0, v0, v5
	v_and_b32_e32 v5, 0xffff0000, v70
	v_add_f32_e32 v1, v1, v4
	v_mul_f32_e32 v1, v1, v5
	v_lshlrev_b32_e32 v5, 16, v71
	v_add_f32_e32 v2, v2, v4
	v_mul_f32_e32 v2, v2, v5
	v_and_b32_e32 v5, 0xffff0000, v71
	v_add_f32_e32 v3, v3, v4
	v_mul_f32_e32 v3, v3, v5
	v_cvt_pk_bf16_f32 v0, v0, v1
	v_cvt_pk_bf16_f32 v1, v2, v3
	global_store_dwordx2 v[68:69], v[0:1], off offset:96
	s_cbranch_scc1 .LBB0_958

.LBB0_1193:
	s_add_i32 s9, s2, 0xffffe000
	s_ashr_i32 s10, s7, 5
	s_and_b32 s8, s2, 0xffffffc0
	s_lshr_b32 s9, s9, 12
	s_lshl_b32 s11, s10, 8
	s_cmpk_lt_i32 s8, 0x2000
	s_cselect_b32 s9, s10, s9
	s_cselect_b32 s12, 8, 12
	s_lshl_b32 s9, s9, 12
	s_addk_i32 s9, 0x2000
	s_cmpk_lt_i32 s8, 0x2000
	s_movk_i32 s10, 0xfc0
	s_cselect_b32 s13, 0xc0, s10
	s_cselect_b32 s10, s11, s9
	s_ashr_i32 s11, s10, 31
	s_and_b32 s9, s13, s2
	s_lshl_b64 s[10:11], s[10:11], 10
	s_add_u32 s10, s0, s10
	s_addc_u32 s11, s1, s11
	s_lshl_b32 s9, s9, 1
	s_add_u32 s10, s10, s9
	s_addc_u32 s11, s11, 0
	s_and_b32 s9, s6, 0x100
	v_add_u32_e32 v8, s9, v0
	v_ashrrev_i32_e32 v9, 31, v8
	v_lshlrev_b64 v[10:11], s12, v[8:9]
	v_add_u32_e32 v12, 64, v8
	v_add_u32_e32 v14, 0x80, v8
	v_add_u32_e32 v8, 0xc0, v8
	v_lshl_add_u64 v[6:7], s[10:11], 0, v[164:165]
	v_ashrrev_i32_e32 v13, 31, v12
	v_ashrrev_i32_e32 v15, 31, v14
	v_ashrrev_i32_e32 v9, 31, v8
	v_lshl_add_u64 v[10:11], v[10:11], 1, v[6:7]
	v_lshlrev_b64 v[12:13], s12, v[12:13]
	v_lshlrev_b64 v[14:15], s12, v[14:15]
	v_lshlrev_b64 v[8:9], s12, v[8:9]
	s_barrier
	v_lshl_add_u64 v[12:13], v[12:13], 1, v[6:7]
	v_lshl_add_u64 v[14:15], v[14:15], 1, v[6:7]
	v_lshl_add_u64 v[16:17], v[8:9], 1, v[6:7]
	global_load_dwordx4 v[6:9], v[10:11], off
	global_load_dwordx4 v[198:201], v[12:13], off
	global_load_dwordx4 v[202:205], v[14:15], off
	global_load_dwordx4 v[206:209], v[16:17], off
	s_lshl_b32 s48, s9, 1
	s_add_i32 s7, s7, s22
	s_add_i32 s6, s6, s14
	s_add_i32 s2, s2, s15
	s_cmpk_lt_i32 s7, 0x1400
	s_waitcnt vmcnt(3)
	ds_write_b128 v1, v[6:9]
	s_waitcnt vmcnt(2)
	ds_write_b128 v3, v[198:201]
	s_waitcnt vmcnt(1)
	ds_write_b128 v4, v[202:205]
	s_waitcnt vmcnt(0)
	ds_write_b128 v5, v[206:209]
	v_add_u32_e32 v6, s8, v0
	v_ashrrev_i32_e32 v7, 31, v6
	v_lshlrev_b64 v[6:7], 11, v[6:7]
	v_lshl_add_u64 v[6:7], s[4:5], 0, v[6:7]
	s_waitcnt lgkmcnt(0)
	s_barrier
	v_lshl_add_u64 v[10:11], v[6:7], 0, v[164:165]
	ds_read_u16 v6, v2
	ds_read_u16 v7, v2 offset:144
	v_lshl_add_u64 v[10:11], v[10:11], 0, s[48:49]
	s_mov_b64 s[8:9], 0x15078400
	s_waitcnt lgkmcnt(0)
	v_lshl_or_b32 v6, v7, 16, v6
	ds_read_u16 v7, v2 offset:288
	ds_read_u16 v8, v2 offset:432
	s_waitcnt lgkmcnt(0)
	v_lshl_or_b32 v7, v8, 16, v7
	ds_read_u16 v8, v2 offset:576
	ds_read_u16 v9, v2 offset:720
	s_waitcnt lgkmcnt(0)
	v_lshl_or_b32 v8, v9, 16, v8
	ds_read_u16 v9, v2 offset:864
	ds_read_u16 v12, v2 offset:1008
	s_waitcnt lgkmcnt(0)
	v_lshl_or_b32 v9, v12, 16, v9
	v_lshl_add_u64 v[12:13], v[10:11], 0, s[8:9]
	s_mov_b32 s8, 0x15078000
	v_add_co_u32_e32 v10, vcc, s8, v10
	s_nop 1
	v_addc_co_u32_e32 v11, vcc, 0, v11, vcc
	global_store_dwordx4 v[10:11], v[6:9], off offset:1024
	ds_read_u16 v6, v2 offset:9216
	ds_read_u16 v7, v2 offset:9360
	s_waitcnt lgkmcnt(0)
	v_lshl_or_b32 v6, v7, 16, v6
	ds_read_u16 v7, v2 offset:9504
	ds_read_u16 v8, v2 offset:9648
	s_waitcnt lgkmcnt(0)
	v_lshl_or_b32 v7, v8, 16, v7
	ds_read_u16 v8, v2 offset:9792
	ds_read_u16 v9, v2 offset:9936
	s_waitcnt lgkmcnt(0)
	v_lshl_or_b32 v8, v9, 16, v8
	ds_read_u16 v9, v2 offset:10080
	ds_read_u16 v10, v2 offset:10224
	s_waitcnt lgkmcnt(0)
	v_lshl_or_b32 v9, v10, 16, v9
	global_store_dwordx4 v[12:13], v[6:9], off offset:128
	ds_read_u16 v6, v2 offset:18432
	ds_read_u16 v7, v2 offset:18576
	s_waitcnt lgkmcnt(0)
	v_lshl_or_b32 v6, v7, 16, v6
	ds_read_u16 v7, v2 offset:18720
	ds_read_u16 v8, v2 offset:18864
	s_waitcnt lgkmcnt(0)
	v_lshl_or_b32 v7, v8, 16, v7
	ds_read_u16 v8, v2 offset:19008
	ds_read_u16 v9, v2 offset:19152
	s_waitcnt lgkmcnt(0)
	v_lshl_or_b32 v8, v9, 16, v8
	ds_read_u16 v9, v2 offset:19296
	ds_read_u16 v10, v2 offset:19440
	s_waitcnt lgkmcnt(0)
	v_lshl_or_b32 v9, v10, 16, v9
	global_store_dwordx4 v[12:13], v[6:9], off offset:256
	ds_read_u16 v6, v2 offset:27648
	ds_read_u16 v7, v2 offset:27792
	s_waitcnt lgkmcnt(0)
	v_lshl_or_b32 v6, v7, 16, v6
	ds_read_u16 v7, v2 offset:27936
	ds_read_u16 v8, v2 offset:28080
	s_waitcnt lgkmcnt(0)
	v_lshl_or_b32 v7, v8, 16, v7
	ds_read_u16 v8, v2 offset:28224
	ds_read_u16 v9, v2 offset:28368
	s_waitcnt lgkmcnt(0)
	v_lshl_or_b32 v8, v9, 16, v8
	ds_read_u16 v9, v2 offset:28512
	ds_read_u16 v10, v2 offset:28656
	s_waitcnt lgkmcnt(0)
	v_lshl_or_b32 v9, v10, 16, v9
	global_store_dwordx4 v[12:13], v[6:9], off offset:384
	s_cbranch_scc1 .LBB0_1193

.LBB0_1250:
	s_lshr_b32 s1, s15, 1
	s_lshl_b32 s0, s0, 8
	s_and_b32 s1, s1, 0x60
	v_and_b32_e32 v98, 15, v96
	s_or_b32 s0, s1, s0
	v_lshrrev_b32_e32 v96, 2, v96
	v_and_or_b32 v96, v96, 12, s0
	s_lshl_b64 s[0:1], s[40:41], 12
	s_add_u32 s0, s38, s0
	s_addc_u32 s1, s39, s1
	s_lshr_b32 s6, s48, 12
	s_add_i32 s11, s6, 1
	s_and_b64 s[6:7], s[36:37], exec
	s_cselect_b32 s6, 0, s11
	s_mul_hi_u32 s7, s6, 0x6000
	s_mulk_i32 s6, 0x6000
	v_ashrrev_i32_e32 v97, 31, v96
	s_add_u32 s6, s2, s6
	s_addc_u32 s7, s22, s7
	v_lshlrev_b64 v[146:147], 2, v[96:97]
	v_lshl_add_u64 v[186:187], s[6:7], 0, v[146:147]
	s_ashr_i32 s6, s15, 2
	s_andn2_b32 s6, s6, 63
	v_or_b32_e32 v152, s6, v98
	v_ashrrev_i32_e32 v153, 31, v152
	v_lshl_add_u64 v[150:151], s[0:1], 0, v[146:147]
	v_lshlrev_b64 v[96:97], 12, v[152:153]
	v_lshl_add_u64 v[142:143], v[150:151], 0, v[96:97]
	v_or_b32_e32 v96, 16, v152
	v_ashrrev_i32_e32 v97, 31, v96
	v_lshlrev_b64 v[96:97], 12, v[96:97]
	s_add_i32 s6, s6, s10
	v_lshl_add_u64 v[96:97], v[150:151], 0, v[96:97]
	v_or_b32_e32 v148, s6, v98
	global_load_dwordx4 v[156:159], v[142:143], off nt
	global_load_dwordx4 v[160:163], v[142:143], off offset:64 nt
	global_load_dwordx4 v[166:169], v[142:143], off offset:512 nt
	global_load_dwordx4 v[170:173], v[142:143], off offset:576 nt
	global_load_dwordx4 v[174:177], v[96:97], off nt
	global_load_dwordx4 v[178:181], v[96:97], off offset:64 nt
	global_load_dwordx4 v[182:185], v[96:97], off offset:512 nt
	global_load_dwordx4 v[198:201], v[96:97], off offset:576 nt
	v_ashrrev_i32_e32 v149, 31, v148
	global_load_dwordx4 v[96:99], v[186:187], off
	global_load_dwordx4 v[202:205], v[186:187], off offset:64
	global_load_dwordx4 v[206:209], v[186:187], off offset:512
	global_load_dwordx4 v[210:213], v[186:187], off offset:576
	v_lshlrev_b64 v[144:145], 12, v[148:149]
	v_lshl_add_u64 v[144:145], s[4:5], 0, v[144:145]
	v_lshl_add_u64 v[144:145], v[144:145], 0, v[146:147]
	s_mov_b32 s0, 0x80000
	s_mov_b64 s[6:7], 0x80000
	s_mov_b32 s1, 0x90000
	s_mov_b64 s[10:11], 0x90000
	s_mov_b32 s67, 0xb0000
	s_mov_b64 s[36:37], s[20:21]
	s_waitcnt vmcnt(0)
	v_pk_fma_f32 v[158:159], v[102:103], v[98:99], v[158:159]
	v_pk_fma_f32 v[156:157], v[100:101], v[96:97], v[156:157]
	v_mov_b32_e32 v100, v202
	v_mov_b32_e32 v101, v203
	v_mov_b32_e32 v102, v204
	v_mov_b32_e32 v103, v205
	v_pk_fma_f32 v[162:163], v[106:107], v[102:103], v[162:163]
	v_pk_fma_f32 v[160:161], v[104:105], v[100:101], v[160:161]
	v_mov_b32_e32 v104, v206
	v_mov_b32_e32 v105, v207
	v_mov_b32_e32 v106, v208
	v_mov_b32_e32 v107, v209
	v_pk_fma_f32 v[168:169], v[110:111], v[106:107], v[168:169]
	v_pk_fma_f32 v[166:167], v[108:109], v[104:105], v[166:167]
	v_mov_b32_e32 v108, v210
	v_mov_b32_e32 v109, v211
	v_mov_b32_e32 v110, v212
	v_mov_b32_e32 v111, v213
	s_nop 0
	global_store_dwordx4 v[144:145], v[156:159], off nt
	global_store_dwordx4 v[144:145], v[160:163], off offset:64 nt
	global_store_dwordx4 v[144:145], v[166:169], off offset:512 nt
	v_pk_fma_f32 v[118:119], v[118:119], v[106:107], v[184:185]
	v_pk_fma_f32 v[116:117], v[116:117], v[104:105], v[182:183]
	v_or_b32_e32 v166, 32, v148
	v_ashrrev_i32_e32 v167, 31, v166
	v_lshlrev_b64 v[166:167], 12, v[166:167]
	v_lshl_add_u64 v[166:167], s[4:5], 0, v[166:167]
	v_lshl_add_u64 v[166:167], v[166:167], 0, v[146:147]
	v_pk_fma_f32 v[122:123], v[122:123], v[110:111], v[172:173]
	v_pk_fma_f32 v[120:121], v[120:121], v[108:109], v[170:171]
	global_store_dwordx4 v[144:145], v[120:123], off offset:576 nt
	v_pk_fma_f32 v[114:115], v[114:115], v[110:111], v[200:201]
	v_pk_fma_f32 v[112:113], v[112:113], v[108:109], v[198:199]
	v_or_b32_e32 v120, 16, v148
	v_ashrrev_i32_e32 v121, 31, v120
	v_lshlrev_b64 v[120:121], 12, v[120:121]
	v_lshl_add_u64 v[120:121], s[4:5], 0, v[120:121]
	v_lshl_add_u64 v[156:157], v[120:121], 0, v[146:147]
	global_store_dwordx4 v[156:157], v[112:115], off offset:576 nt
	v_pk_fma_f32 v[122:123], v[130:131], v[98:99], v[176:177]
	v_pk_fma_f32 v[120:121], v[128:129], v[96:97], v[174:175]
	v_or_b32_e32 v112, 32, v152
	v_ashrrev_i32_e32 v113, 31, v112
	global_store_dwordx4 v[156:157], v[120:123], off nt
	v_lshlrev_b64 v[112:113], 12, v[112:113]
	global_store_dwordx4 v[156:157], v[116:119], off offset:512 nt
	v_pk_fma_f32 v[122:123], v[126:127], v[102:103], v[180:181]
	v_pk_fma_f32 v[120:121], v[124:125], v[100:101], v[178:179]
	global_store_dwordx4 v[156:157], v[120:123], off offset:64 nt
	v_lshl_add_u64 v[124:125], v[150:151], 0, v[112:113]
	global_load_dwordx4 v[112:115], v[124:125], off nt
	global_load_dwordx4 v[116:119], v[124:125], off offset:64 nt
	global_load_dwordx4 v[120:123], v[124:125], off offset:512 nt
	s_nop 0
	global_load_dwordx4 v[124:127], v[124:125], off offset:576 nt
	v_or_b32_e32 v128, 48, v152
	v_ashrrev_i32_e32 v129, 31, v128
	v_lshlrev_b64 v[128:129], 12, v[128:129]
	v_lshl_add_u64 v[160:161], v[150:151], 0, v[128:129]
	global_load_dwordx4 v[128:131], v[160:161], off nt
	global_load_dwordx4 v[150:153], v[160:161], off offset:64 nt
	global_load_dwordx4 v[156:159], v[160:161], off offset:512 nt
	s_nop 0
	global_load_dwordx4 v[160:163], v[160:161], off offset:576 nt
	s_waitcnt vmcnt(0)
	v_pk_fma_f32 v[94:95], v[94:95], v[98:99], v[114:115]
	v_pk_fma_f32 v[92:93], v[92:93], v[96:97], v[112:113]
	v_pk_fma_f32 v[90:91], v[90:91], v[102:103], v[118:119]
	v_pk_fma_f32 v[82:83], v[82:83], v[110:111], v[126:127]
	v_pk_fma_f32 v[80:81], v[80:81], v[108:109], v[124:125]
	global_store_dwordx4 v[166:167], v[80:83], off offset:576 nt
	v_pk_fma_f32 v[88:89], v[88:89], v[100:101], v[116:117]
	v_pk_fma_f32 v[86:87], v[86:87], v[106:107], v[122:123]
	v_or_b32_e32 v80, 48, v148
	v_ashrrev_i32_e32 v81, 31, v80
	v_lshlrev_b64 v[80:81], 12, v[80:81]
	v_lshl_add_u64 v[80:81], s[4:5], 0, v[80:81]
	v_lshl_add_u64 v[80:81], v[80:81], 0, v[146:147]
	v_pk_fma_f32 v[66:67], v[66:67], v[110:111], v[162:163]
	v_pk_fma_f32 v[64:65], v[64:65], v[108:109], v[160:161]
	global_store_dwordx4 v[80:81], v[64:67], off offset:576 nt
	v_pk_fma_f32 v[84:85], v[84:85], v[104:105], v[120:121]
	v_pk_fma_f32 v[78:79], v[78:79], v[98:99], v[130:131]
	v_add_co_u32_e32 v64, vcc, s0, v142
	v_pk_fma_f32 v[76:77], v[76:77], v[96:97], v[128:129]
	v_pk_fma_f32 v[74:75], v[74:75], v[102:103], v[152:153]
	v_pk_fma_f32 v[72:73], v[72:73], v[100:101], v[150:151]
	v_pk_fma_f32 v[70:71], v[70:71], v[106:107], v[158:159]
	v_pk_fma_f32 v[68:69], v[68:69], v[104:105], v[156:157]
	v_addc_co_u32_e32 v65, vcc, 0, v143, vcc
	global_store_dwordx4 v[166:167], v[92:95], off nt
	global_store_dwordx4 v[166:167], v[88:91], off offset:64 nt
	global_store_dwordx4 v[166:167], v[84:87], off offset:512 nt
	global_store_dwordx4 v[80:81], v[76:79], off nt
	global_store_dwordx4 v[80:81], v[72:75], off offset:64 nt
	global_store_dwordx4 v[80:81], v[68:71], off offset:512 nt
	v_lshl_add_u64 v[76:77], v[142:143], 0, s[6:7]
	v_add_co_u32_e32 v80, vcc, s1, v142
	global_load_dwordx4 v[64:67], v[64:65], off nt
	s_nop 0
	global_load_dwordx4 v[68:71], v[76:77], off offset:64 nt
	global_load_dwordx4 v[72:75], v[76:77], off offset:512 nt
	s_nop 0
	global_load_dwordx4 v[76:79], v[76:77], off offset:576 nt
	v_lshl_add_u64 v[92:93], v[142:143], 0, s[10:11]
	v_addc_co_u32_e32 v81, vcc, 0, v143, vcc
	global_load_dwordx4 v[80:83], v[80:81], off nt
	s_nop 0
	global_load_dwordx4 v[84:87], v[92:93], off offset:64 nt
	global_load_dwordx4 v[88:91], v[92:93], off offset:512 nt
	s_nop 0
	global_load_dwordx4 v[92:95], v[92:93], off offset:576 nt
	v_lshl_add_u64 v[112:113], v[144:145], 0, s[6:7]
	s_mov_b64 s[6:7], 0xa0000
	s_waitcnt vmcnt(0)
	v_pk_fma_f32 v[60:61], v[60:61], v[96:97], v[64:65]
	v_add_co_u32_e32 v64, vcc, s0, v144
	v_pk_fma_f32 v[46:47], v[46:47], v[106:107], v[74:75]
	s_nop 0
	v_addc_co_u32_e32 v65, vcc, 0, v145, vcc
	v_pk_fma_f32 v[44:45], v[44:45], v[104:105], v[72:73]
	global_store_dwordx4 v[112:113], v[44:47], off offset:512 nt
	v_pk_fma_f32 v[42:43], v[42:43], v[110:111], v[78:79]
	v_pk_fma_f32 v[40:41], v[40:41], v[108:109], v[76:77]
	v_add_co_u32_e32 v46, vcc, s1, v144
	global_store_dwordx4 v[112:113], v[40:43], off offset:576 nt
	v_lshl_add_u64 v[44:45], v[144:145], 0, s[10:11]
	v_addc_co_u32_e32 v47, vcc, 0, v145, vcc
	v_pk_fma_f32 v[42:43], v[54:55], v[98:99], v[82:83]
	v_pk_fma_f32 v[40:41], v[52:53], v[96:97], v[80:81]
	v_pk_fma_f32 v[34:35], v[34:35], v[110:111], v[94:95]
	v_pk_fma_f32 v[32:33], v[32:33], v[108:109], v[92:93]
	s_mov_b32 s0, 0xa0000
	v_pk_fma_f32 v[62:63], v[62:63], v[98:99], v[66:67]
	v_pk_fma_f32 v[58:59], v[58:59], v[102:103], v[70:71]
	v_pk_fma_f32 v[56:57], v[56:57], v[100:101], v[68:69]
	global_store_dwordx4 v[46:47], v[40:43], off nt
	v_pk_fma_f32 v[38:39], v[38:39], v[106:107], v[90:91]
	v_pk_fma_f32 v[36:37], v[36:37], v[104:105], v[88:89]
	v_pk_fma_f32 v[42:43], v[50:51], v[102:103], v[86:87]
	v_pk_fma_f32 v[40:41], v[48:49], v[100:101], v[84:85]
	global_store_dwordx4 v[44:45], v[32:35], off offset:576 nt
	global_store_dwordx4 v[64:65], v[60:63], off nt
	global_store_dwordx4 v[112:113], v[56:59], off offset:64 nt
	v_add_co_u32_e32 v32, vcc, s0, v142
	global_store_dwordx4 v[44:45], v[40:43], off offset:64 nt
	global_store_dwordx4 v[44:45], v[36:39], off offset:512 nt
	v_lshl_add_u64 v[44:45], v[142:143], 0, s[6:7]
	v_addc_co_u32_e32 v33, vcc, 0, v143, vcc
	s_mov_b32 s1, 0xb0000
	global_load_dwordx4 v[32:35], v[32:33], off nt
	s_nop 0
	global_load_dwordx4 v[36:39], v[44:45], off offset:64 nt
	global_load_dwordx4 v[40:43], v[44:45], off offset:512 nt
	s_nop 0
	global_load_dwordx4 v[44:47], v[44:45], off offset:576 nt
	s_mov_b64 s[10:11], 0xb0000
	v_add_co_u32_e32 v48, vcc, s1, v142
	v_lshl_add_u64 v[60:61], v[142:143], 0, s[10:11]
	s_nop 0
	v_addc_co_u32_e32 v49, vcc, 0, v143, vcc
	global_load_dwordx4 v[48:51], v[48:49], off nt
	s_nop 0
	global_load_dwordx4 v[52:55], v[60:61], off offset:64 nt
	global_load_dwordx4 v[56:59], v[60:61], off offset:512 nt
	s_nop 0
	global_load_dwordx4 v[60:63], v[60:61], off offset:576 nt
	v_lshl_add_u64 v[64:65], v[144:145], 0, s[6:7]
	s_waitcnt vmcnt(0)
	v_pk_fma_f32 v[28:29], v[28:29], v[96:97], v[32:33]
	v_add_co_u32_e32 v32, vcc, s0, v144
	v_pk_fma_f32 v[14:15], v[14:15], v[106:107], v[42:43]
	s_nop 0
	v_addc_co_u32_e32 v33, vcc, 0, v145, vcc
	v_pk_fma_f32 v[12:13], v[12:13], v[104:105], v[40:41]
	global_store_dwordx4 v[64:65], v[12:15], off offset:512 nt
	v_pk_fma_f32 v[10:11], v[10:11], v[110:111], v[46:47]
	v_pk_fma_f32 v[8:9], v[8:9], v[108:109], v[44:45]
	v_add_co_u32_e32 v14, vcc, s1, v144
	global_store_dwordx4 v[64:65], v[8:11], off offset:576 nt
	s_nop 0
	v_addc_co_u32_e32 v15, vcc, 0, v145, vcc
	v_pk_fma_f32 v[10:11], v[22:23], v[98:99], v[50:51]
	v_pk_fma_f32 v[8:9], v[20:21], v[96:97], v[48:49]
	v_pk_fma_f32 v[30:31], v[30:31], v[98:99], v[34:35]
	v_pk_fma_f32 v[26:27], v[26:27], v[102:103], v[38:39]
	v_pk_fma_f32 v[24:25], v[24:25], v[100:101], v[36:37]
	v_lshl_add_u64 v[12:13], v[144:145], 0, s[10:11]
	global_store_dwordx4 v[14:15], v[8:11], off nt
	v_pk_fma_f32 v[6:7], v[6:7], v[106:107], v[58:59]
	v_pk_fma_f32 v[4:5], v[4:5], v[104:105], v[56:57]
	v_pk_fma_f32 v[10:11], v[18:19], v[102:103], v[54:55]
	v_pk_fma_f32 v[8:9], v[16:17], v[100:101], v[52:53]
	v_pk_fma_f32 v[2:3], v[2:3], v[110:111], v[62:63]
	v_pk_fma_f32 v[0:1], v[0:1], v[108:109], v[60:61]
	s_and_b64 vcc, exec, s[34:35]
	s_mov_b32 s1, s14
	s_mov_b32 s0, s16
	s_mov_b64 s[10:11], s[30:31]
	global_store_dwordx4 v[32:33], v[28:31], off nt
	global_store_dwordx4 v[64:65], v[24:27], off offset:64 nt
	global_store_dwordx4 v[12:13], v[8:11], off offset:64 nt
	global_store_dwordx4 v[12:13], v[4:7], off offset:512 nt
	global_store_dwordx4 v[12:13], v[0:3], off offset:576 nt
	s_cbranch_vccnz .LBB0_1267

.LBB0_1549:
	s_add_u32 s14, s10, 0x4000
	s_addc_u32 s15, s11, 0
	s_cmp_eq_u32 s51, 40
	s_cselect_b32 s20, s4, s14
	s_cselect_b32 s21, s5, s15
	s_cselect_b32 s14, s8, s48
	s_cselect_b32 s15, s9, s50
	s_add_u32 s16, s20, 0x8000
	s_addc_u32 s17, s21, 0
	s_add_i32 s52, 0, 0x10000
	v_add_u32_e32 v146, s52, v150
	ds_read_b128 v[96:99], v146
	ds_read_b128 v[138:141], v146 offset:1024
	ds_read_b128 v[142:145], v146 offset:2048
	ds_read_b128 v[146:149], v146 offset:3072
	v_lshl_add_u64 v[186:187], s[10:11], 0, v[134:135]
	s_add_i32 m0, s37, 0xc000
	ds_read_b128 v[152:155], v151
	ds_read_b128 v[156:159], v151 offset:1024
	ds_read_b128 v[160:163], v151 offset:2048
	ds_read_b128 v[166:169], v151 offset:3072
	ds_read_b128 v[170:173], v151 offset:4096
	ds_read_b128 v[174:177], v151 offset:5120
	ds_read_b128 v[178:181], v151 offset:6144
	ds_read_b128 v[182:185], v151 offset:7168
	global_load_lds_dwordx4 v[186:187], off
	v_lshl_add_u64 v[186:187], s[10:11], 0, v[136:137]
	s_add_i32 m0, s37, 0xe000
	s_nop 0
	global_load_lds_dwordx4 v[186:187], off
	s_waitcnt lgkmcnt(8)
	s_barrier
	s_waitcnt lgkmcnt(0)
	s_setprio 1
	s_waitcnt lgkmcnt(0)
	v_mfma_f32_16x16x32_bf16 v[100:103], v[96:99], v[152:155], v[100:103]
	v_mfma_f32_16x16x32_bf16 v[104:107], v[142:145], v[152:155], v[104:107]
	v_mfma_f32_16x16x32_bf16 v[128:131], v[96:99], v[160:163], v[128:131]
	v_mfma_f32_16x16x32_bf16 v[124:127], v[142:145], v[160:163], v[124:127]
	v_mfma_f32_16x16x32_bf16 v[92:95], v[96:99], v[170:173], v[92:95]
	v_mfma_f32_16x16x32_bf16 v[88:91], v[142:145], v[170:173], v[88:91]
	v_mfma_f32_16x16x32_bf16 v[76:79], v[96:99], v[178:181], v[76:79]
	v_mfma_f32_16x16x32_bf16 v[72:75], v[142:145], v[178:181], v[72:75]
	v_mfma_f32_16x16x32_bf16 v[100:103], v[138:141], v[156:159], v[100:103]
	v_mfma_f32_16x16x32_bf16 v[104:107], v[146:149], v[156:159], v[104:107]
	v_mfma_f32_16x16x32_bf16 v[128:131], v[138:141], v[166:169], v[128:131]
	v_mfma_f32_16x16x32_bf16 v[124:127], v[146:149], v[166:169], v[124:127]
	v_mfma_f32_16x16x32_bf16 v[92:95], v[138:141], v[174:177], v[92:95]
	v_mfma_f32_16x16x32_bf16 v[88:91], v[146:149], v[174:177], v[88:91]
	v_mfma_f32_16x16x32_bf16 v[76:79], v[138:141], v[182:185], v[76:79]
	v_mfma_f32_16x16x32_bf16 v[72:75], v[146:149], v[182:185], v[72:75]
	s_setprio 0
	s_barrier
	s_add_i32 s58, 0, 0x14000
	v_add_u32_e32 v186, s58, v150
	s_add_i32 s52, s52, s36
	ds_read_b128 v[198:201], v186
	ds_read_b128 v[202:205], v186 offset:1024
	ds_read_b128 v[206:209], v186 offset:2048
	ds_read_b128 v[210:213], v186 offset:3072
	v_lshl_add_u64 v[186:187], s[14:15], 0, v[164:165]
	s_mov_b32 m0, s52
	s_nop 0
	global_load_lds_dwordx4 v[186:187], off
	v_lshl_add_u64 v[186:187], s[14:15], 0, v[132:133]
	s_add_i32 m0, s52, 0x2000
	s_nop 0
	global_load_lds_dwordx4 v[186:187], off
	s_barrier
	s_waitcnt lgkmcnt(0)
	s_setprio 1
	s_waitcnt lgkmcnt(0)
	v_mfma_f32_16x16x32_bf16 v[108:111], v[198:201], v[152:155], v[108:111]
	v_mfma_f32_16x16x32_bf16 v[120:123], v[206:209], v[152:155], v[120:123]
	v_mfma_f32_16x16x32_bf16 v[116:119], v[198:201], v[160:163], v[116:119]
	v_mfma_f32_16x16x32_bf16 v[112:115], v[206:209], v[160:163], v[112:115]
	v_mfma_f32_16x16x32_bf16 v[84:87], v[198:201], v[170:173], v[84:87]
	v_mfma_f32_16x16x32_bf16 v[80:83], v[206:209], v[170:173], v[80:83]
	v_mfma_f32_16x16x32_bf16 v[68:71], v[198:201], v[178:181], v[68:71]
	v_mfma_f32_16x16x32_bf16 v[64:67], v[206:209], v[178:181], v[64:67]
	v_mfma_f32_16x16x32_bf16 v[108:111], v[202:205], v[156:159], v[108:111]
	v_mfma_f32_16x16x32_bf16 v[120:123], v[210:213], v[156:159], v[120:123]
	v_mfma_f32_16x16x32_bf16 v[116:119], v[202:205], v[166:169], v[116:119]
	v_mfma_f32_16x16x32_bf16 v[112:115], v[210:213], v[166:169], v[112:115]
	v_mfma_f32_16x16x32_bf16 v[84:87], v[202:205], v[174:177], v[84:87]
	v_mfma_f32_16x16x32_bf16 v[80:83], v[210:213], v[174:177], v[80:83]
	v_mfma_f32_16x16x32_bf16 v[68:71], v[202:205], v[182:185], v[68:71]
	v_mfma_f32_16x16x32_bf16 v[64:67], v[210:213], v[182:185], v[64:67]
	s_setprio 0
	s_mov_b32 m0, s37
	v_lshl_add_u64 v[186:187], s[20:21], 0, v[164:165]
	s_barrier
	ds_read_b128 v[152:155], v151 offset:16384
	ds_read_b128 v[156:159], v151 offset:17408
	ds_read_b128 v[160:163], v151 offset:18432
	ds_read_b128 v[166:169], v151 offset:19456
	ds_read_b128 v[170:173], v151 offset:20480
	ds_read_b128 v[174:177], v151 offset:21504
	ds_read_b128 v[178:181], v151 offset:22528
	ds_read_b128 v[182:185], v151 offset:23552
	global_load_lds_dwordx4 v[186:187], off
	v_lshl_add_u64 v[186:187], s[20:21], 0, v[132:133]
	s_mov_b32 m0, s38
	s_nop 0
	global_load_lds_dwordx4 v[186:187], off
	s_barrier
	s_waitcnt lgkmcnt(0)
	s_setprio 1
	s_waitcnt lgkmcnt(0)
	v_mfma_f32_16x16x32_bf16 v[60:63], v[96:99], v[152:155], v[60:63]
	v_mfma_f32_16x16x32_bf16 v[56:59], v[142:145], v[152:155], v[56:59]
	v_mfma_f32_16x16x32_bf16 v[52:55], v[96:99], v[160:163], v[52:55]
	v_mfma_f32_16x16x32_bf16 v[48:51], v[142:145], v[160:163], v[48:51]
	v_mfma_f32_16x16x32_bf16 v[28:31], v[96:99], v[170:173], v[28:31]
	v_mfma_f32_16x16x32_bf16 v[24:27], v[142:145], v[170:173], v[24:27]
	v_mfma_f32_16x16x32_bf16 v[20:23], v[96:99], v[178:181], v[20:23]
	v_mfma_f32_16x16x32_bf16 v[16:19], v[142:145], v[178:181], v[16:19]
	v_mfma_f32_16x16x32_bf16 v[60:63], v[138:141], v[156:159], v[60:63]
	v_mfma_f32_16x16x32_bf16 v[56:59], v[146:149], v[156:159], v[56:59]
	v_mfma_f32_16x16x32_bf16 v[52:55], v[138:141], v[166:169], v[52:55]
	v_mfma_f32_16x16x32_bf16 v[48:51], v[146:149], v[166:169], v[48:51]
	v_mfma_f32_16x16x32_bf16 v[28:31], v[138:141], v[174:177], v[28:31]
	v_mfma_f32_16x16x32_bf16 v[24:27], v[146:149], v[174:177], v[24:27]
	v_mfma_f32_16x16x32_bf16 v[20:23], v[138:141], v[182:185], v[20:23]
	v_mfma_f32_16x16x32_bf16 v[16:19], v[146:149], v[182:185], v[16:19]
	s_setprio 0
	s_barrier
	s_add_u32 s52, s14, 0x4000
	s_addc_u32 s53, s15, 0
	s_add_i32 s58, s58, s36
	v_lshl_add_u64 v[96:97], s[52:53], 0, v[164:165]
	s_mov_b32 m0, s58
	s_nop 0
	global_load_lds_dwordx4 v[96:97], off
	v_lshl_add_u64 v[96:97], s[52:53], 0, v[132:133]
	s_add_i32 m0, s58, 0x2000
	s_nop 0
	global_load_lds_dwordx4 v[96:97], off
	s_waitcnt vmcnt(6)
	s_barrier
	s_setprio 1
	v_mfma_f32_16x16x32_bf16 v[44:47], v[198:201], v[152:155], v[44:47]
	v_mfma_f32_16x16x32_bf16 v[40:43], v[206:209], v[152:155], v[40:43]
	v_mfma_f32_16x16x32_bf16 v[36:39], v[198:201], v[160:163], v[36:39]
	v_mfma_f32_16x16x32_bf16 v[32:35], v[206:209], v[160:163], v[32:35]
	v_mfma_f32_16x16x32_bf16 v[12:15], v[198:201], v[170:173], v[12:15]
	v_mfma_f32_16x16x32_bf16 v[8:11], v[206:209], v[170:173], v[8:11]
	v_mfma_f32_16x16x32_bf16 v[4:7], v[198:201], v[178:181], v[4:7]
	v_mfma_f32_16x16x32_bf16 v[0:3], v[206:209], v[178:181], v[0:3]
	v_mfma_f32_16x16x32_bf16 v[44:47], v[202:205], v[156:159], v[44:47]
	v_mfma_f32_16x16x32_bf16 v[40:43], v[210:213], v[156:159], v[40:43]
	v_mfma_f32_16x16x32_bf16 v[36:39], v[202:205], v[166:169], v[36:39]
	v_mfma_f32_16x16x32_bf16 v[32:35], v[210:213], v[166:169], v[32:35]
	v_mfma_f32_16x16x32_bf16 v[12:15], v[202:205], v[174:177], v[12:15]
	v_mfma_f32_16x16x32_bf16 v[8:11], v[210:213], v[174:177], v[8:11]
	v_mfma_f32_16x16x32_bf16 v[4:7], v[202:205], v[182:185], v[4:7]
	v_mfma_f32_16x16x32_bf16 v[0:3], v[210:213], v[182:185], v[0:3]
	s_setprio 0
	s_add_i32 s52, 0, 0x18000
	v_add_u32_e32 v146, s52, v150
	s_barrier
	ds_read_b128 v[96:99], v146
	ds_read_b128 v[138:141], v146 offset:1024
	ds_read_b128 v[142:145], v146 offset:2048
	ds_read_b128 v[146:149], v146 offset:3072
	s_add_u32 s20, s20, 0x4000
	s_addc_u32 s21, s21, 0
	s_mov_b32 m0, s39
	v_lshl_add_u64 v[186:187], s[20:21], 0, v[164:165]
	ds_read_b128 v[152:155], v151 offset:32768
	ds_read_b128 v[156:159], v151 offset:33792
	ds_read_b128 v[160:163], v151 offset:34816
	ds_read_b128 v[166:169], v151 offset:35840
	ds_read_b128 v[170:173], v151 offset:36864
	ds_read_b128 v[174:177], v151 offset:37888
	ds_read_b128 v[178:181], v151 offset:38912
	ds_read_b128 v[182:185], v151 offset:39936
	global_load_lds_dwordx4 v[186:187], off
	v_lshl_add_u64 v[186:187], s[20:21], 0, v[132:133]
	s_mov_b32 m0, s40
	s_nop 0
	global_load_lds_dwordx4 v[186:187], off
	s_waitcnt lgkmcnt(8)
	s_barrier
	s_waitcnt lgkmcnt(0)
	s_setprio 1
	s_waitcnt lgkmcnt(0)
	v_mfma_f32_16x16x32_bf16 v[100:103], v[96:99], v[152:155], v[100:103]
	v_mfma_f32_16x16x32_bf16 v[104:107], v[142:145], v[152:155], v[104:107]
	v_mfma_f32_16x16x32_bf16 v[128:131], v[96:99], v[160:163], v[128:131]
	v_mfma_f32_16x16x32_bf16 v[124:127], v[142:145], v[160:163], v[124:127]
	v_mfma_f32_16x16x32_bf16 v[92:95], v[96:99], v[170:173], v[92:95]
	v_mfma_f32_16x16x32_bf16 v[88:91], v[142:145], v[170:173], v[88:91]
	v_mfma_f32_16x16x32_bf16 v[76:79], v[96:99], v[178:181], v[76:79]
	v_mfma_f32_16x16x32_bf16 v[72:75], v[142:145], v[178:181], v[72:75]
	v_mfma_f32_16x16x32_bf16 v[100:103], v[138:141], v[156:159], v[100:103]
	v_mfma_f32_16x16x32_bf16 v[104:107], v[146:149], v[156:159], v[104:107]
	v_mfma_f32_16x16x32_bf16 v[128:131], v[138:141], v[166:169], v[128:131]
	v_mfma_f32_16x16x32_bf16 v[124:127], v[146:149], v[166:169], v[124:127]
	v_mfma_f32_16x16x32_bf16 v[92:95], v[138:141], v[174:177], v[92:95]
	v_mfma_f32_16x16x32_bf16 v[88:91], v[146:149], v[174:177], v[88:91]
	v_mfma_f32_16x16x32_bf16 v[76:79], v[138:141], v[182:185], v[76:79]
	v_mfma_f32_16x16x32_bf16 v[72:75], v[146:149], v[182:185], v[72:75]
	s_setprio 0
	s_barrier
	s_add_i32 s53, 0, 0x1c000
	s_add_u32 s20, s14, 0x8000
	v_add_u32_e32 v186, s53, v150
	s_addc_u32 s21, s15, 0
	s_add_i32 s52, s52, s36
	ds_read_b128 v[198:201], v186
	ds_read_b128 v[202:205], v186 offset:1024
	ds_read_b128 v[206:209], v186 offset:2048
	ds_read_b128 v[210:213], v186 offset:3072
	v_lshl_add_u64 v[186:187], s[20:21], 0, v[164:165]
	s_mov_b32 m0, s52
	s_nop 0
	global_load_lds_dwordx4 v[186:187], off
	v_lshl_add_u64 v[186:187], s[20:21], 0, v[132:133]
	s_add_i32 m0, s52, 0x2000
	s_nop 0
	global_load_lds_dwordx4 v[186:187], off
	s_barrier
	s_waitcnt lgkmcnt(0)
	s_setprio 1
	s_waitcnt lgkmcnt(0)
	v_mfma_f32_16x16x32_bf16 v[108:111], v[198:201], v[152:155], v[108:111]
	v_mfma_f32_16x16x32_bf16 v[120:123], v[206:209], v[152:155], v[120:123]
	v_mfma_f32_16x16x32_bf16 v[116:119], v[198:201], v[160:163], v[116:119]
	v_mfma_f32_16x16x32_bf16 v[112:115], v[206:209], v[160:163], v[112:115]
	v_mfma_f32_16x16x32_bf16 v[84:87], v[198:201], v[170:173], v[84:87]
	v_mfma_f32_16x16x32_bf16 v[80:83], v[206:209], v[170:173], v[80:83]
	v_mfma_f32_16x16x32_bf16 v[68:71], v[198:201], v[178:181], v[68:71]
	v_mfma_f32_16x16x32_bf16 v[64:67], v[206:209], v[178:181], v[64:67]
	v_mfma_f32_16x16x32_bf16 v[108:111], v[202:205], v[156:159], v[108:111]
	v_mfma_f32_16x16x32_bf16 v[120:123], v[210:213], v[156:159], v[120:123]
	v_mfma_f32_16x16x32_bf16 v[116:119], v[202:205], v[166:169], v[116:119]
	v_mfma_f32_16x16x32_bf16 v[112:115], v[210:213], v[166:169], v[112:115]
	v_mfma_f32_16x16x32_bf16 v[84:87], v[202:205], v[174:177], v[84:87]
	v_mfma_f32_16x16x32_bf16 v[80:83], v[210:213], v[174:177], v[80:83]
	v_mfma_f32_16x16x32_bf16 v[68:71], v[202:205], v[182:185], v[68:71]
	v_mfma_f32_16x16x32_bf16 v[64:67], v[210:213], v[182:185], v[64:67]
	s_setprio 0
	s_mov_b32 m0, s41
	v_lshl_add_u64 v[186:187], s[16:17], 0, v[164:165]
	s_barrier
	ds_read_b128 v[152:155], v151 offset:49152
	ds_read_b128 v[156:159], v151 offset:50176
	ds_read_b128 v[160:163], v151 offset:51200
	ds_read_b128 v[166:169], v151 offset:52224
	ds_read_b128 v[170:173], v151 offset:53248
	ds_read_b128 v[174:177], v151 offset:54272
	ds_read_b128 v[178:181], v151 offset:55296
	ds_read_b128 v[182:185], v151 offset:56320
	global_load_lds_dwordx4 v[186:187], off
	v_lshl_add_u64 v[186:187], s[16:17], 0, v[132:133]
	s_mov_b32 m0, s42
	s_nop 0
	global_load_lds_dwordx4 v[186:187], off
	s_barrier
	s_waitcnt lgkmcnt(0)
	s_setprio 1
	s_waitcnt lgkmcnt(0)
	v_mfma_f32_16x16x32_bf16 v[60:63], v[96:99], v[152:155], v[60:63]
	v_mfma_f32_16x16x32_bf16 v[56:59], v[142:145], v[152:155], v[56:59]
	v_mfma_f32_16x16x32_bf16 v[52:55], v[96:99], v[160:163], v[52:55]
	v_mfma_f32_16x16x32_bf16 v[48:51], v[142:145], v[160:163], v[48:51]
	v_mfma_f32_16x16x32_bf16 v[28:31], v[96:99], v[170:173], v[28:31]
	v_mfma_f32_16x16x32_bf16 v[24:27], v[142:145], v[170:173], v[24:27]
	v_mfma_f32_16x16x32_bf16 v[20:23], v[96:99], v[178:181], v[20:23]
	v_mfma_f32_16x16x32_bf16 v[16:19], v[142:145], v[178:181], v[16:19]
	v_mfma_f32_16x16x32_bf16 v[60:63], v[138:141], v[156:159], v[60:63]
	v_mfma_f32_16x16x32_bf16 v[56:59], v[146:149], v[156:159], v[56:59]
	v_mfma_f32_16x16x32_bf16 v[52:55], v[138:141], v[166:169], v[52:55]
	v_mfma_f32_16x16x32_bf16 v[48:51], v[146:149], v[166:169], v[48:51]
	v_mfma_f32_16x16x32_bf16 v[28:31], v[138:141], v[174:177], v[28:31]
	v_mfma_f32_16x16x32_bf16 v[24:27], v[146:149], v[174:177], v[24:27]
	v_mfma_f32_16x16x32_bf16 v[20:23], v[138:141], v[182:185], v[20:23]
	v_mfma_f32_16x16x32_bf16 v[16:19], v[146:149], v[182:185], v[16:19]
	s_setprio 0
	s_barrier
	s_add_u32 s14, s14, 0xc000
	s_addc_u32 s15, s15, 0
	s_add_i32 s16, s53, s36
	v_lshl_add_u64 v[96:97], s[14:15], 0, v[164:165]
	s_mov_b32 m0, s16
	s_nop 0
	global_load_lds_dwordx4 v[96:97], off
	v_lshl_add_u64 v[96:97], s[14:15], 0, v[132:133]
	s_add_i32 m0, s16, 0x2000
	s_nop 0
	global_load_lds_dwordx4 v[96:97], off
	s_waitcnt vmcnt(6)
	s_barrier
	s_setprio 1
	v_mfma_f32_16x16x32_bf16 v[44:47], v[198:201], v[152:155], v[44:47]
	v_mfma_f32_16x16x32_bf16 v[40:43], v[206:209], v[152:155], v[40:43]
	v_mfma_f32_16x16x32_bf16 v[36:39], v[198:201], v[160:163], v[36:39]
	v_mfma_f32_16x16x32_bf16 v[32:35], v[206:209], v[160:163], v[32:35]
	v_mfma_f32_16x16x32_bf16 v[12:15], v[198:201], v[170:173], v[12:15]
	v_mfma_f32_16x16x32_bf16 v[8:11], v[206:209], v[170:173], v[8:11]
	v_mfma_f32_16x16x32_bf16 v[4:7], v[198:201], v[178:181], v[4:7]
	v_mfma_f32_16x16x32_bf16 v[0:3], v[206:209], v[178:181], v[0:3]
	v_mfma_f32_16x16x32_bf16 v[44:47], v[202:205], v[156:159], v[44:47]
	v_mfma_f32_16x16x32_bf16 v[40:43], v[210:213], v[156:159], v[40:43]
	v_mfma_f32_16x16x32_bf16 v[36:39], v[202:205], v[166:169], v[36:39]
	v_mfma_f32_16x16x32_bf16 v[32:35], v[210:213], v[166:169], v[32:35]
	v_mfma_f32_16x16x32_bf16 v[12:15], v[202:205], v[174:177], v[12:15]
	v_mfma_f32_16x16x32_bf16 v[8:11], v[210:213], v[174:177], v[8:11]
	v_mfma_f32_16x16x32_bf16 v[4:7], v[202:205], v[182:185], v[4:7]
	v_mfma_f32_16x16x32_bf16 v[0:3], v[210:213], v[182:185], v[0:3]
	s_setprio 0
	s_add_i32 s51, s51, 2
	s_add_u32 s10, s10, 0x10000
	s_addc_u32 s11, s11, 0
	s_add_u32 s48, s48, 0x10000
	s_addc_u32 s50, s50, 0
	s_cmp_gt_u32 s51, 41
	s_barrier
	s_cbranch_scc0 .LBB0_1549
	v_mov_b32_e32 v96, v188
	s_lshl_b32 s11, s47, 8
	v_readfirstlane_b32 s20, v96
	s_lshr_b32 s14, s20, 1
	s_and_b32 s14, s14, 0x60
	v_and_b32_e32 v98, 15, v96
	s_lshl_b32 s10, s46, 8
	s_or_b32 s11, s14, s11
	v_lshrrev_b32_e32 v96, 2, v96
	v_and_or_b32 v96, v96, 12, s11
	s_ashr_i32 s11, s10, 31
	s_add_i32 s16, s10, 0xffffe000
	s_lshl_b64 s[14:15], s[10:11], 12
	s_add_u32 s14, s0, s14
	s_addc_u32 s15, s1, s15
	s_lshr_b32 s11, s16, 12
	s_add_i32 s11, s11, 1
	s_cmp_gt_i32 s46, 31
	s_cselect_b32 s11, s11, 0
	s_mul_hi_u32 s17, s11, 0x6000
	s_mulk_i32 s11, 0x6000
	s_add_u32 s16, s2, s11
	s_addc_u32 s17, s6, s17
	s_ashr_i32 s11, s20, 2
	s_andn2_b32 s11, s11, 63
	v_ashrrev_i32_e32 v97, 31, v96
	v_or_b32_e32 v148, s11, v98
	v_lshlrev_b64 v[142:143], 2, v[96:97]
	v_ashrrev_i32_e32 v149, 31, v148
	v_lshl_add_u64 v[146:147], s[14:15], 0, v[142:143]
	v_lshlrev_b64 v[96:97], 12, v[148:149]
	v_lshl_add_u64 v[138:139], v[146:147], 0, v[96:97]
	v_or_b32_e32 v96, 16, v148
	v_ashrrev_i32_e32 v97, 31, v96
	v_lshlrev_b64 v[96:97], 12, v[96:97]
	v_lshl_add_u64 v[186:187], s[16:17], 0, v[142:143]
	s_add_i32 s11, s11, s10
	v_lshl_add_u64 v[96:97], v[146:147], 0, v[96:97]
	v_or_b32_e32 v144, s11, v98
	global_load_dwordx4 v[152:155], v[138:139], off nt
	global_load_dwordx4 v[156:159], v[138:139], off offset:64 nt
	global_load_dwordx4 v[160:163], v[138:139], off offset:512 nt
	global_load_dwordx4 v[166:169], v[138:139], off offset:576 nt
	global_load_dwordx4 v[170:173], v[96:97], off nt
	global_load_dwordx4 v[174:177], v[96:97], off offset:64 nt
	global_load_dwordx4 v[178:181], v[96:97], off offset:512 nt
	global_load_dwordx4 v[182:185], v[96:97], off offset:576 nt
	v_ashrrev_i32_e32 v145, 31, v144
	global_load_dwordx4 v[96:99], v[186:187], off
	global_load_dwordx4 v[202:205], v[186:187], off offset:64
	global_load_dwordx4 v[206:209], v[186:187], off offset:512
	global_load_dwordx4 v[210:213], v[186:187], off offset:576
	v_lshlrev_b64 v[140:141], 12, v[144:145]
	v_lshl_add_u64 v[140:141], s[0:1], 0, v[140:141]
	v_lshl_add_u64 v[140:141], v[140:141], 0, v[142:143]
	s_mov_b32 s10, 0x80000
	s_mov_b64 s[14:15], 0x80000
	s_mov_b32 s11, 0x90000
	s_mov_b64 s[16:17], 0x90000
	v_readlane_b32 s52, v236, 11
	s_mov_b32 s67, 0xb0000
	s_mov_b32 s46, s45
	s_mov_b32 s47, s44
	s_movk_i32 s50, 0x6000
	s_movk_i32 s48, 0x1fff
	v_readlane_b32 s53, v236, 12
	s_mov_b64 s[58:59], 0x1000
	s_waitcnt vmcnt(0)
	v_pk_fma_f32 v[154:155], v[102:103], v[98:99], v[154:155]
	v_pk_fma_f32 v[152:153], v[100:101], v[96:97], v[152:153]
	v_mov_b32_e32 v100, v202
	v_mov_b32_e32 v101, v203
	v_mov_b32_e32 v102, v204
	v_mov_b32_e32 v103, v205
	v_pk_fma_f32 v[158:159], v[106:107], v[102:103], v[158:159]
	v_pk_fma_f32 v[156:157], v[104:105], v[100:101], v[156:157]
	v_mov_b32_e32 v104, v206
	v_mov_b32_e32 v105, v207
	v_mov_b32_e32 v106, v208
	v_mov_b32_e32 v107, v209
	v_pk_fma_f32 v[162:163], v[110:111], v[106:107], v[162:163]
	v_pk_fma_f32 v[160:161], v[108:109], v[104:105], v[160:161]
	v_mov_b32_e32 v108, v210
	v_mov_b32_e32 v109, v211
	v_mov_b32_e32 v110, v212
	v_mov_b32_e32 v111, v213
	s_nop 0
	global_store_dwordx4 v[140:141], v[152:155], off nt
	global_store_dwordx4 v[140:141], v[156:159], off offset:64 nt
	global_store_dwordx4 v[140:141], v[160:163], off offset:512 nt
	v_pk_fma_f32 v[118:119], v[118:119], v[106:107], v[180:181]
	v_pk_fma_f32 v[116:117], v[116:117], v[104:105], v[178:179]
	v_or_b32_e32 v160, 32, v144
	v_ashrrev_i32_e32 v161, 31, v160
	v_lshlrev_b64 v[160:161], 12, v[160:161]
	v_lshl_add_u64 v[160:161], s[0:1], 0, v[160:161]
	v_lshl_add_u64 v[160:161], v[160:161], 0, v[142:143]
	v_pk_fma_f32 v[122:123], v[122:123], v[110:111], v[168:169]
	v_pk_fma_f32 v[120:121], v[120:121], v[108:109], v[166:167]
	global_store_dwordx4 v[140:141], v[120:123], off offset:576 nt
	v_pk_fma_f32 v[114:115], v[114:115], v[110:111], v[184:185]
	v_pk_fma_f32 v[112:113], v[112:113], v[108:109], v[182:183]
	v_or_b32_e32 v120, 16, v144
	v_ashrrev_i32_e32 v121, 31, v120
	v_lshlrev_b64 v[120:121], 12, v[120:121]
	v_lshl_add_u64 v[120:121], s[0:1], 0, v[120:121]
	v_lshl_add_u64 v[152:153], v[120:121], 0, v[142:143]
	global_store_dwordx4 v[152:153], v[112:115], off offset:576 nt
	v_pk_fma_f32 v[122:123], v[130:131], v[98:99], v[172:173]
	v_pk_fma_f32 v[120:121], v[128:129], v[96:97], v[170:171]
	v_or_b32_e32 v112, 32, v148
	v_ashrrev_i32_e32 v113, 31, v112
	global_store_dwordx4 v[152:153], v[120:123], off nt
	v_lshlrev_b64 v[112:113], 12, v[112:113]
	global_store_dwordx4 v[152:153], v[116:119], off offset:512 nt
	v_pk_fma_f32 v[122:123], v[126:127], v[102:103], v[176:177]
	v_pk_fma_f32 v[120:121], v[124:125], v[100:101], v[174:175]
	global_store_dwordx4 v[152:153], v[120:123], off offset:64 nt
	v_lshl_add_u64 v[124:125], v[146:147], 0, v[112:113]
	global_load_dwordx4 v[112:115], v[124:125], off nt
	global_load_dwordx4 v[116:119], v[124:125], off offset:64 nt
	global_load_dwordx4 v[120:123], v[124:125], off offset:512 nt
	s_nop 0
	global_load_dwordx4 v[124:127], v[124:125], off offset:576 nt
	v_or_b32_e32 v128, 48, v148
	v_ashrrev_i32_e32 v129, 31, v128
	v_lshlrev_b64 v[128:129], 12, v[128:129]
	v_lshl_add_u64 v[156:157], v[146:147], 0, v[128:129]
	global_load_dwordx4 v[128:131], v[156:157], off nt
	global_load_dwordx4 v[146:149], v[156:157], off offset:64 nt
	global_load_dwordx4 v[152:155], v[156:157], off offset:512 nt
	s_nop 0
	global_load_dwordx4 v[156:159], v[156:157], off offset:576 nt
	s_waitcnt vmcnt(0)
	v_pk_fma_f32 v[94:95], v[94:95], v[98:99], v[114:115]
	v_pk_fma_f32 v[92:93], v[92:93], v[96:97], v[112:113]
	v_pk_fma_f32 v[90:91], v[90:91], v[102:103], v[118:119]
	v_pk_fma_f32 v[82:83], v[82:83], v[110:111], v[126:127]
	v_pk_fma_f32 v[80:81], v[80:81], v[108:109], v[124:125]
	global_store_dwordx4 v[160:161], v[80:83], off offset:576 nt
	v_pk_fma_f32 v[88:89], v[88:89], v[100:101], v[116:117]
	v_pk_fma_f32 v[86:87], v[86:87], v[106:107], v[122:123]
	v_or_b32_e32 v80, 48, v144
	v_ashrrev_i32_e32 v81, 31, v80
	v_lshlrev_b64 v[80:81], 12, v[80:81]
	v_lshl_add_u64 v[80:81], s[0:1], 0, v[80:81]
	v_lshl_add_u64 v[80:81], v[80:81], 0, v[142:143]
	v_pk_fma_f32 v[66:67], v[66:67], v[110:111], v[158:159]
	v_pk_fma_f32 v[64:65], v[64:65], v[108:109], v[156:157]
	global_store_dwordx4 v[80:81], v[64:67], off offset:576 nt
	v_pk_fma_f32 v[84:85], v[84:85], v[104:105], v[120:121]
	v_pk_fma_f32 v[78:79], v[78:79], v[98:99], v[130:131]
	v_add_co_u32_e32 v64, vcc, s10, v138
	v_pk_fma_f32 v[76:77], v[76:77], v[96:97], v[128:129]
	v_pk_fma_f32 v[74:75], v[74:75], v[102:103], v[148:149]
	v_pk_fma_f32 v[72:73], v[72:73], v[100:101], v[146:147]
	v_pk_fma_f32 v[70:71], v[70:71], v[106:107], v[154:155]
	v_pk_fma_f32 v[68:69], v[68:69], v[104:105], v[152:153]
	v_addc_co_u32_e32 v65, vcc, 0, v139, vcc
	global_store_dwordx4 v[160:161], v[92:95], off nt
	global_store_dwordx4 v[160:161], v[88:91], off offset:64 nt
	global_store_dwordx4 v[160:161], v[84:87], off offset:512 nt
	global_store_dwordx4 v[80:81], v[76:79], off nt
	global_store_dwordx4 v[80:81], v[72:75], off offset:64 nt
	global_store_dwordx4 v[80:81], v[68:71], off offset:512 nt
	v_lshl_add_u64 v[76:77], v[138:139], 0, s[14:15]
	v_add_co_u32_e32 v80, vcc, s11, v138
	global_load_dwordx4 v[64:67], v[64:65], off nt
	s_nop 0
	global_load_dwordx4 v[68:71], v[76:77], off offset:64 nt
	global_load_dwordx4 v[72:75], v[76:77], off offset:512 nt
	s_nop 0
	global_load_dwordx4 v[76:79], v[76:77], off offset:576 nt
	v_lshl_add_u64 v[92:93], v[138:139], 0, s[16:17]
	v_addc_co_u32_e32 v81, vcc, 0, v139, vcc
	global_load_dwordx4 v[80:83], v[80:81], off nt
	s_nop 0
	global_load_dwordx4 v[84:87], v[92:93], off offset:64 nt
	global_load_dwordx4 v[88:91], v[92:93], off offset:512 nt
	s_nop 0
	global_load_dwordx4 v[92:95], v[92:93], off offset:576 nt
	v_lshl_add_u64 v[112:113], v[140:141], 0, s[14:15]
	s_mov_b64 s[14:15], 0xa0000
	s_waitcnt vmcnt(0)
	v_pk_fma_f32 v[60:61], v[60:61], v[96:97], v[64:65]
	v_add_co_u32_e32 v64, vcc, s10, v140
	v_pk_fma_f32 v[46:47], v[46:47], v[106:107], v[74:75]
	s_nop 0
	v_addc_co_u32_e32 v65, vcc, 0, v141, vcc
	v_pk_fma_f32 v[44:45], v[44:45], v[104:105], v[72:73]
	global_store_dwordx4 v[112:113], v[44:47], off offset:512 nt
	v_pk_fma_f32 v[42:43], v[42:43], v[110:111], v[78:79]
	v_pk_fma_f32 v[40:41], v[40:41], v[108:109], v[76:77]
	v_add_co_u32_e32 v46, vcc, s11, v140
	global_store_dwordx4 v[112:113], v[40:43], off offset:576 nt
	v_lshl_add_u64 v[44:45], v[140:141], 0, s[16:17]
	v_addc_co_u32_e32 v47, vcc, 0, v141, vcc
	v_pk_fma_f32 v[42:43], v[54:55], v[98:99], v[82:83]
	v_pk_fma_f32 v[40:41], v[52:53], v[96:97], v[80:81]
	v_pk_fma_f32 v[34:35], v[34:35], v[110:111], v[94:95]
	v_pk_fma_f32 v[32:33], v[32:33], v[108:109], v[92:93]
	s_mov_b32 s10, 0xa0000
	v_pk_fma_f32 v[62:63], v[62:63], v[98:99], v[66:67]
	v_pk_fma_f32 v[58:59], v[58:59], v[102:103], v[70:71]
	v_pk_fma_f32 v[56:57], v[56:57], v[100:101], v[68:69]
	global_store_dwordx4 v[46:47], v[40:43], off nt
	v_pk_fma_f32 v[38:39], v[38:39], v[106:107], v[90:91]
	v_pk_fma_f32 v[36:37], v[36:37], v[104:105], v[88:89]
	v_pk_fma_f32 v[42:43], v[50:51], v[102:103], v[86:87]
	v_pk_fma_f32 v[40:41], v[48:49], v[100:101], v[84:85]
	global_store_dwordx4 v[44:45], v[32:35], off offset:576 nt
	global_store_dwordx4 v[64:65], v[60:63], off nt
	global_store_dwordx4 v[112:113], v[56:59], off offset:64 nt
	v_add_co_u32_e32 v32, vcc, s10, v138
	global_store_dwordx4 v[44:45], v[40:43], off offset:64 nt
	global_store_dwordx4 v[44:45], v[36:39], off offset:512 nt
	v_lshl_add_u64 v[44:45], v[138:139], 0, s[14:15]
	v_addc_co_u32_e32 v33, vcc, 0, v139, vcc
	s_mov_b32 s11, 0xb0000
	global_load_dwordx4 v[32:35], v[32:33], off nt
	s_nop 0
	global_load_dwordx4 v[36:39], v[44:45], off offset:64 nt
	global_load_dwordx4 v[40:43], v[44:45], off offset:512 nt
	s_nop 0
	global_load_dwordx4 v[44:47], v[44:45], off offset:576 nt
	s_mov_b64 s[16:17], 0xb0000
	v_add_co_u32_e32 v48, vcc, s11, v138
	v_lshl_add_u64 v[60:61], v[138:139], 0, s[16:17]
	s_nop 0
	v_addc_co_u32_e32 v49, vcc, 0, v139, vcc
	global_load_dwordx4 v[48:51], v[48:49], off nt
	s_nop 0
	global_load_dwordx4 v[52:55], v[60:61], off offset:64 nt
	global_load_dwordx4 v[56:59], v[60:61], off offset:512 nt
	s_nop 0
	global_load_dwordx4 v[60:63], v[60:61], off offset:576 nt
	v_lshl_add_u64 v[64:65], v[140:141], 0, s[14:15]
	s_mov_b64 s[14:15], s[8:9]
	s_waitcnt vmcnt(0)
	v_pk_fma_f32 v[28:29], v[28:29], v[96:97], v[32:33]
	v_add_co_u32_e32 v32, vcc, s10, v140
	v_pk_fma_f32 v[14:15], v[14:15], v[106:107], v[42:43]
	s_nop 0
	v_addc_co_u32_e32 v33, vcc, 0, v141, vcc
	v_pk_fma_f32 v[12:13], v[12:13], v[104:105], v[40:41]
	global_store_dwordx4 v[64:65], v[12:15], off offset:512 nt
	v_pk_fma_f32 v[10:11], v[10:11], v[110:111], v[46:47]
	v_pk_fma_f32 v[8:9], v[8:9], v[108:109], v[44:45]
	v_add_co_u32_e32 v14, vcc, s11, v140
	global_store_dwordx4 v[64:65], v[8:11], off offset:576 nt
	s_nop 0
	v_addc_co_u32_e32 v15, vcc, 0, v141, vcc
	v_pk_fma_f32 v[10:11], v[22:23], v[98:99], v[50:51]
	v_pk_fma_f32 v[8:9], v[20:21], v[96:97], v[48:49]
	v_pk_fma_f32 v[30:31], v[30:31], v[98:99], v[34:35]
	v_pk_fma_f32 v[26:27], v[26:27], v[102:103], v[38:39]
	v_pk_fma_f32 v[24:25], v[24:25], v[100:101], v[36:37]
	v_lshl_add_u64 v[12:13], v[140:141], 0, s[16:17]
	global_store_dwordx4 v[14:15], v[8:11], off nt
	v_pk_fma_f32 v[6:7], v[6:7], v[106:107], v[58:59]
	v_pk_fma_f32 v[4:5], v[4:5], v[104:105], v[56:57]
	v_pk_fma_f32 v[10:11], v[18:19], v[102:103], v[54:55]
	v_pk_fma_f32 v[8:9], v[16:17], v[100:101], v[52:53]
	v_pk_fma_f32 v[2:3], v[2:3], v[110:111], v[62:63]
	v_pk_fma_f32 v[0:1], v[0:1], v[108:109], v[60:61]
	s_and_b64 vcc, exec, s[12:13]
	s_mov_b32 s12, s45
	s_mov_b32 s13, s44
	s_mov_b64 s[10:11], s[4:5]
	v_readlane_b32 s44, v236, 3
	global_store_dwordx4 v[32:33], v[28:31], off nt
	global_store_dwordx4 v[64:65], v[24:27], off offset:64 nt
	global_store_dwordx4 v[12:13], v[8:11], off offset:64 nt
	global_store_dwordx4 v[12:13], v[4:7], off offset:512 nt
	global_store_dwordx4 v[12:13], v[0:3], off offset:576 nt
	v_readlane_b32 s45, v236, 4
	s_cbranch_vccz .LBB0_1541
	s_branch .LBB0_1555
